# GEMM ring v3: barrier mid-MFMA-block, next-step LDS reads hidden behind MFMAs, DMA interleaved; compress MLP K-loop software-pipelined 4 deep
# speedup vs baseline: 1.0100x; 1.0100x over previous
; template <int EPI> ...
;     ...
;     const int idx0 = blockIdx.x >> 3;
;     if (idx0 < perX) {
;         int mt0, nt0; tile_of(idx0, mt0, nt0);
;         const bf16_t* A0 = A + (size_t)(mt0 * 128 + lrow) * K + lcc * 8;
;         const bf16_t* B0 = Bt + (size_t)(nt0 * 256 + lrowp) * K + lcc * 8;
;         G_LOAD(A0, B0, 0);
;         G_STORE(0);
;         G_LOAD(A0, B0, 1);
;         __syncthreads();
;     }
;     for (int idx = idx0; idx < perX; idx += nbx) {
;         int mt, nt; tile_of(idx, mt, nt);
;         int mtn, ntn; tile_of(idx + nbx < perX ? idx + nbx : idx, mtn, ntn);
;         const bf16_t* Ag = A + (size_t)(mt * 128 + lrow) * K + lcc * 8;
;         const bf16_t* Bg = Bt + (size_t)(nt * 256 + lrowp) * K + lcc * 8;
;         const bf16_t* An = A + (size_t)(mtn * 128 + lrow) * K + lcc * 8;
;         const bf16_t* Bn = Bt + (size_t)(ntn * 256 + lrowp) * K + lcc * 8;
;         f32x4 acc[4][8];
; #pragma unroll
;         for (int i = 0; i < 4; ++i)
; #pragma unroll
;             for (int j = 0; j < 8; ++j) {
;                 if (EPI == 2)
;                     acc[i][j] = *(const f32x4*)(xin + (size_t)(mt * 128 + wr * 64 + i * 16 + fr) * Nn + nt * 256 + wc * 128 + 32 * (j >> 1) + 8 * fq + 4 * (j & 1));
;                 else acc[i][j] = (f32x4){0.f, 0.f, 0.f, 0.f};
;             }
;         for (int kt = 0; kt < nk; ++kt) {
;             const int buf = kt & 1;
;             const bf16_t* a_ = sA + buf * 128 * 40 + (wr * 64 + fr) * 40 + fq * 8;
;             const bf16_t* b_ = sB + buf * 256 * 40 + (wc * 128 + fr) * 40 + fq * 8;
;             bf16x8 af[4];
; #pragma unroll
;             for (int i = 0; i < 4; ++i) af[i] = *(const bf16x8*)(a_ + i * 16 * 40);
; #pragma unroll
;             for (int jh = 0; jh < 2; ++jh) {
;                 bf16x8 bfr[4];
; #pragma unroll
;                 for (int j = 0; j < 4; ++j) bfr[j] = *(const bf16x8*)(b_ + (jh * 4 + j) * 16 * 40);
; #pragma unroll
;                 for (int i = 0; i < 4; ++i)
; #pragma unroll
;                     for (int j = 0; j < 4; ++j) acc[i][jh * 4 + j] = mfma(bfr[j], af[i], acc[i][jh * 4 + j]);
;             }
;             G_STORE(buf ^ 1);
;             {
;                 const bool cur = kt + 2 < nk;
;                 const bf16_t* pa = cur ? Ag : An; const bf16_t* pb = cur ? Bg : Bn;
;                 const int st = cur ? kt + 2 : kt + 2 - nk;
;                 G_LOAD(pa, pb, st);
.LBB0_162:
	v_readlane_b32 s9, v253, 4
	v_readlane_b32 s12, v253, 6
	v_readlane_b32 s13, v253, 5
	s_nop 3
	s_cmp_eq_u32 s13, 0
	s_cbranch_scc1 .Lg162_entry
	v_and_b32_e32 v8, 63, v210
	v_lshrrev_b32_e32 v9, 6, v210
	s_nop 0
	v_readfirstlane_b32 s13, v9
	v_lshrrev_b32_e32 v9, 4, v8
	v_sub_u32_e32 v10, 0, v9
	v_and_b32_e32 v10, 3, v10
	v_and_b32_e32 v11, 3, v8
	v_xor_b32_e32 v11, v11, v10
	v_lshrrev_b32_e32 v12, 2, v8
	v_lshlrev_b32_e32 v0, 11, v12
	v_lshl_add_u32 v0, v11, 4, v0
	s_lshl_b32 vcc_lo, s13, 16
	v_add_u32_e32 v0, vcc_lo, v0
	v_add_u32_e32 v0, 0x1000, v0
	v_add_u32_e32 v1, 0x7c00, v0
	v_and_b32_e32 v13, 3, v12
	v_lshl_add_u32 v13, v9, 3, v13
	v_lshlrev_b32_e32 v2, 11, v13
	v_lshl_add_u32 v2, v11, 4, v2
	s_lshl_b32 vcc_lo, s13, 17
	v_add_u32_e32 v2, vcc_lo, v2
	v_add_u32_e32 v2, 0x800, v2
	v_add_u32_e32 v3, 0x1c00, v2
	v_add_u32_e32 v4, 0x10800, v2
	v_add_u32_e32 v5, 0x12400, v2
	v_and_b32_e32 v10, 15, v8
	v_lshrrev_b32_e32 v11, 2, v10
	v_sub_u32_e32 v11, 0, v11
	v_and_b32_e32 v11, 3, v11
	v_xor_b32_e32 v11, v9, v11
	v_lshlrev_b32_e32 v6, 6, v10
	v_lshl_add_u32 v6, v11, 4, v6
	s_lshr_b32 vcc_lo, s13, 1
	s_mul_i32 vcc_lo, vcc_lo, 0x3000
	s_and_b32 vcc_hi, s13, 1
	s_mul_i32 vcc_hi, vcc_hi, 0x3000
	s_add_u32 vcc_hi, vcc_hi, 0x800
	v_add_u32_e32 v7, vcc_hi, v6
	v_add_u32_e32 v6, vcc_lo, v6
	s_mul_i32 s12, s13, 0x1800
	v_writelane_b32 v253, s12, 6
	v_writelane_b32 v253, 0, 5
	v_readlane_b32 vcc_lo, v253, 0
	v_readlane_b32 vcc_hi, v253, 1
	s_lshl_b32 s13, s6, 18
	s_nop 1
	s_add_u32 s98, vcc_lo, s13
	s_addc_u32 s99, vcc_hi, 0
	s_sub_u32 s98, s98, 0x1000
	s_subb_u32 s99, s99, 0
	v_readlane_b32 vcc_lo, v253, 2
	v_readlane_b32 vcc_hi, v253, 3
	s_lshl_b32 s13, s5, 19
	s_nop 1
	s_add_u32 s100, vcc_lo, s13
	s_addc_u32 s101, vcc_hi, 0
	s_sub_u32 s100, s100, 0x1000
	s_subb_u32 s101, s101, 0
	s_add_u32 m0, s9, s12
	s_nop 0
	global_load_lds_dwordx4 v0, s[98:99]
	global_load_lds_dwordx4 v1, s[98:99] offset:1024
	global_load_lds_dwordx4 v2, s[100:101] offset:2048
	global_load_lds_dwordx4 v3, s[100:101] offset:3072
	s_add_u32 m0, m0, 0x1000
	s_nop 0
	global_load_lds_dwordx4 v4, s[100:101]
	global_load_lds_dwordx4 v5, s[100:101] offset:1024
	s_add_u32 s98, s98, 64
	s_addc_u32 s99, s99, 0
	s_add_u32 s100, s100, 64
	s_addc_u32 s101, s101, 0
	s_add_u32 s13, s9, 0x6000
	s_cmp_eq_u32 s13, 0x12000
	s_cselect_b32 s13, 0, s13
	s_add_u32 m0, s13, s12
	s_nop 0
	global_load_lds_dwordx4 v0, s[98:99]
	global_load_lds_dwordx4 v1, s[98:99] offset:1024
	global_load_lds_dwordx4 v2, s[100:101] offset:2048
	global_load_lds_dwordx4 v3, s[100:101] offset:3072
	s_add_u32 m0, m0, 0x1000
	s_nop 0
	global_load_lds_dwordx4 v4, s[100:101]
	global_load_lds_dwordx4 v5, s[100:101] offset:1024
	s_add_u32 s98, s98, 64
	s_addc_u32 s99, s99, 0
	s_add_u32 s100, s100, 64
	s_addc_u32 s101, s101, 0
	s_add_u32 s13, s13, 0x6000
	s_cmp_eq_u32 s13, 0x12000
	s_cselect_b32 s13, 0, s13
	s_add_u32 m0, s13, s12
	s_nop 0
	global_load_lds_dwordx4 v0, s[98:99]
	global_load_lds_dwordx4 v1, s[98:99] offset:1024
	global_load_lds_dwordx4 v2, s[100:101] offset:2048
	global_load_lds_dwordx4 v3, s[100:101] offset:3072
	s_add_u32 m0, m0, 0x1000
	s_nop 0
	global_load_lds_dwordx4 v4, s[100:101]
	global_load_lds_dwordx4 v5, s[100:101] offset:1024
	s_add_u32 s98, s98, 64
	s_addc_u32 s99, s99, 0
	s_add_u32 s100, s100, 64
	s_addc_u32 s101, s101, 0
.Lg162_entry:
	s_mov_b32 s4, 0
	s_waitcnt vmcnt(0)
	s_barrier
	v_add_u32_e32 v8, s9, v6
	v_add_u32_e32 v9, s9, v7
	ds_read_b128 v[160:163], v9
	ds_read_b128 v[174:177], v9 offset:1024
	ds_read_b128 v[178:181], v9 offset:2048
	ds_read_b128 v[182:185], v9 offset:3072
	ds_read_b128 v[10:13], v8
	ds_read_b128 v[14:17], v8 offset:1024
	ds_read_b128 v[18:21], v8 offset:6144
	ds_read_b128 v[152:155], v8 offset:7168
	ds_read_b128 v[192:195], v9 offset:6144
	ds_read_b128 v[196:199], v9 offset:7168
	ds_read_b128 v[200:203], v9 offset:8192
	ds_read_b128 v[204:207], v9 offset:9216
.Lg162_top:
	s_waitcnt lgkmcnt(4)
	v_mfma_f32_16x16x32_bf16 v[148:151], v[160:163], v[10:13], v[148:151]
	v_mfma_f32_16x16x32_bf16 v[116:119], v[160:163], v[14:17], v[116:119]
	v_mfma_f32_16x16x32_bf16 v[84:87], v[160:163], v[18:21], v[84:87]
	v_mfma_f32_16x16x32_bf16 v[52:55], v[160:163], v[152:155], v[52:55]
	v_mfma_f32_16x16x32_bf16 v[144:147], v[174:177], v[10:13], v[144:147]
	v_mfma_f32_16x16x32_bf16 v[112:115], v[174:177], v[14:17], v[112:115]
	v_mfma_f32_16x16x32_bf16 v[80:83], v[174:177], v[18:21], v[80:83]
	v_mfma_f32_16x16x32_bf16 v[48:51], v[174:177], v[152:155], v[48:51]
	v_mfma_f32_16x16x32_bf16 v[140:143], v[178:181], v[10:13], v[140:143]
	v_mfma_f32_16x16x32_bf16 v[108:111], v[178:181], v[14:17], v[108:111]
	v_mfma_f32_16x16x32_bf16 v[76:79], v[178:181], v[18:21], v[76:79]
	v_mfma_f32_16x16x32_bf16 v[44:47], v[178:181], v[152:155], v[44:47]
	v_mfma_f32_16x16x32_bf16 v[136:139], v[182:185], v[10:13], v[136:139]
	v_mfma_f32_16x16x32_bf16 v[104:107], v[182:185], v[14:17], v[104:107]
	v_mfma_f32_16x16x32_bf16 v[72:75], v[182:185], v[18:21], v[72:75]
	v_mfma_f32_16x16x32_bf16 v[40:43], v[182:185], v[152:155], v[40:43]
	s_waitcnt vmcnt(6)
	s_waitcnt lgkmcnt(0)
	s_barrier
	s_add_u32 s13, s9, 0x6000
	s_cmp_eq_u32 s13, 0x12000
	s_cselect_b32 s13, 0, s13
	v_add_u32_e32 v8, s13, v6
	v_add_u32_e32 v9, s13, v7
	ds_read_b128 v[160:163], v9
	ds_read_b128 v[174:177], v9 offset:1024
	ds_read_b128 v[178:181], v9 offset:2048
	ds_read_b128 v[182:185], v9 offset:3072
	s_cmp_eq_u32 s4, 29
	s_cbranch_scc1 .Lg162_sw
; DI f32x4 mfma(bf16x8 a, bf16x8 b, f32x4 c) { return __builtin_amdgcn_mfma_f32_16x16x32_bf16(a, b, c, 0, 0, 0); }
; #define G_LOAD(PA, PB, STEP) do { _Pragma("unroll") for (int i_ = 0; i_ < 2; ++i_) ra[i_] = *(const u32x4*)((PA) + (size_t)(64 * i_) * K + (STEP) * 32); \
;         _Pragma("unroll") for (int i_ = 0; i_ < 4; ++i_) rb[i_] = *(const u32x4*)((PB) + (size_t)(64 * i_) * K + (STEP) * 32); } while (0)
; #define G_STORE(BUF) do { _Pragma("unroll") for (int i_ = 0; i_ < 2; ++i_) *(u32x4*)(sA + (BUF) * 128 * 40 + (lrow + 64 * i_) * 40 + lcc * 8) = ra[i_]; \
;         _Pragma("unroll") for (int i_ = 0; i_ < 4; ++i_) *(u32x4*)(sB + (BUF) * 256 * 40 + (lrow + 64 * i_) * 40 + lcc * 8) = rb[i_]; } while (0)
; template <int EPI> ...
;     ...
;         for (int kt = 0; kt < nk; ++kt) {
;             const int buf = kt & 1;
;             const bf16_t* a_ = sA + buf * 128 * 40 + (wr * 64 + fr) * 40 + fq * 8;
;             const bf16_t* b_ = sB + buf * 256 * 40 + (wc * 128 + fr) * 40 + fq * 8;
;             bf16x8 af[4];
; #pragma unroll
;             for (int i = 0; i < 4; ++i) af[i] = *(const bf16x8*)(a_ + i * 16 * 40);
; #pragma unroll
;             for (int jh = 0; jh < 2; ++jh) {
;                 bf16x8 bfr[4];
; #pragma unroll
;                 for (int j = 0; j < 4; ++j) bfr[j] = *(const bf16x8*)(b_ + (jh * 4 + j) * 16 * 40);
; #pragma unroll
;                 for (int i = 0; i < 4; ++i)
; #pragma unroll
;                     for (int j = 0; j < 4; ++j) acc[i][jh * 4 + j] = mfma(bfr[j], af[i], acc[i][jh * 4 + j]);
;             }
;             G_STORE(buf ^ 1);
;             {
;                 const bool cur = kt + 2 < nk;
;                 const bf16_t* pa = cur ? Ag : An; const bf16_t* pb = cur ? Bg : Bn;
;                 const int st = cur ? kt + 2 : kt + 2 - nk;
;                 G_LOAD(pa, pb, st);
;             }
;             __syncthreads();
;         }
;     ...
; #pragma unroll
;         for (int i = 0; i < 4; ++i) {
;             const int m = mt * 128 + wr * 64 + i * 16 + fr;
;             float rsc = 1.f;
;             if (EPI != 2 && rs_in) rsc = rsqrtf(rs_in[m] * (1.f / DM) + 1e-6f);
.Lg162_swret:
	s_add_u32 m0, s9, s12
	v_mfma_f32_16x16x32_bf16 v[132:135], v[192:195], v[10:13], v[132:135]
	global_load_lds_dwordx4 v0, s[98:99]
	v_mfma_f32_16x16x32_bf16 v[128:131], v[196:199], v[10:13], v[128:131]
	v_mfma_f32_16x16x32_bf16 v[124:127], v[200:203], v[10:13], v[124:127]
	global_load_lds_dwordx4 v1, s[98:99] offset:1024
	v_mfma_f32_16x16x32_bf16 v[120:123], v[204:207], v[10:13], v[120:123]
	ds_read_b128 v[10:13], v8
	v_mfma_f32_16x16x32_bf16 v[100:103], v[192:195], v[14:17], v[100:103]
	global_load_lds_dwordx4 v2, s[100:101] offset:2048
	v_mfma_f32_16x16x32_bf16 v[96:99], v[196:199], v[14:17], v[96:99]
	v_mfma_f32_16x16x32_bf16 v[92:95], v[200:203], v[14:17], v[92:95]
	global_load_lds_dwordx4 v3, s[100:101] offset:3072
	v_mfma_f32_16x16x32_bf16 v[88:91], v[204:207], v[14:17], v[88:91]
	ds_read_b128 v[14:17], v8 offset:1024
	v_mfma_f32_16x16x32_bf16 v[68:71], v[192:195], v[18:21], v[68:71]
	s_add_u32 m0, m0, 0x1000
	v_mfma_f32_16x16x32_bf16 v[64:67], v[196:199], v[18:21], v[64:67]
	global_load_lds_dwordx4 v4, s[100:101]
	v_mfma_f32_16x16x32_bf16 v[60:63], v[200:203], v[18:21], v[60:63]
	v_mfma_f32_16x16x32_bf16 v[56:59], v[204:207], v[18:21], v[56:59]
	ds_read_b128 v[18:21], v8 offset:6144
	v_mfma_f32_16x16x32_bf16 v[36:39], v[192:195], v[152:155], v[36:39]
	global_load_lds_dwordx4 v5, s[100:101] offset:1024
	v_mfma_f32_16x16x32_bf16 v[32:35], v[196:199], v[152:155], v[32:35]
	v_mfma_f32_16x16x32_bf16 v[28:31], v[200:203], v[152:155], v[28:31]
	v_mfma_f32_16x16x32_bf16 v[24:27], v[204:207], v[152:155], v[24:27]
	ds_read_b128 v[152:155], v8 offset:7168
	ds_read_b128 v[192:195], v9 offset:6144
	ds_read_b128 v[196:199], v9 offset:7168
	ds_read_b128 v[200:203], v9 offset:8192
	ds_read_b128 v[204:207], v9 offset:9216
	s_add_u32 s98, s98, 64
	s_addc_u32 s99, s99, 0
	s_add_u32 s100, s100, 64
	s_addc_u32 s101, s101, 0
	s_add_u32 s9, s9, 0x6000
	s_cmp_eq_u32 s9, 0x12000
	s_cselect_b32 s9, 0, s9
	s_add_u32 s4, s4, 1
	s_cmp_lt_u32 s4, 31
	s_cbranch_scc1 .Lg162_top
	s_waitcnt lgkmcnt(4)
	v_mfma_f32_16x16x32_bf16 v[148:151], v[160:163], v[10:13], v[148:151]
	v_mfma_f32_16x16x32_bf16 v[116:119], v[160:163], v[14:17], v[116:119]
	v_mfma_f32_16x16x32_bf16 v[84:87], v[160:163], v[18:21], v[84:87]
	v_mfma_f32_16x16x32_bf16 v[52:55], v[160:163], v[152:155], v[52:55]
	v_mfma_f32_16x16x32_bf16 v[144:147], v[174:177], v[10:13], v[144:147]
	v_mfma_f32_16x16x32_bf16 v[112:115], v[174:177], v[14:17], v[112:115]
	v_mfma_f32_16x16x32_bf16 v[80:83], v[174:177], v[18:21], v[80:83]
	v_mfma_f32_16x16x32_bf16 v[48:51], v[174:177], v[152:155], v[48:51]
	v_mfma_f32_16x16x32_bf16 v[140:143], v[178:181], v[10:13], v[140:143]
	v_mfma_f32_16x16x32_bf16 v[108:111], v[178:181], v[14:17], v[108:111]
	v_mfma_f32_16x16x32_bf16 v[76:79], v[178:181], v[18:21], v[76:79]
	v_mfma_f32_16x16x32_bf16 v[44:47], v[178:181], v[152:155], v[44:47]
	v_mfma_f32_16x16x32_bf16 v[136:139], v[182:185], v[10:13], v[136:139]
	v_mfma_f32_16x16x32_bf16 v[104:107], v[182:185], v[14:17], v[104:107]
	v_mfma_f32_16x16x32_bf16 v[72:75], v[182:185], v[18:21], v[72:75]
	v_mfma_f32_16x16x32_bf16 v[40:43], v[182:185], v[152:155], v[40:43]
	s_waitcnt vmcnt(6)
	s_waitcnt lgkmcnt(0)
	s_barrier
	s_add_u32 m0, s9, s12
	v_mfma_f32_16x16x32_bf16 v[132:135], v[192:195], v[10:13], v[132:135]
	global_load_lds_dwordx4 v0, s[98:99]
	v_mfma_f32_16x16x32_bf16 v[128:131], v[196:199], v[10:13], v[128:131]
	v_mfma_f32_16x16x32_bf16 v[124:127], v[200:203], v[10:13], v[124:127]
	global_load_lds_dwordx4 v1, s[98:99] offset:1024
	v_mfma_f32_16x16x32_bf16 v[120:123], v[204:207], v[10:13], v[120:123]
	v_mfma_f32_16x16x32_bf16 v[100:103], v[192:195], v[14:17], v[100:103]
	global_load_lds_dwordx4 v2, s[100:101] offset:2048
	v_mfma_f32_16x16x32_bf16 v[96:99], v[196:199], v[14:17], v[96:99]
	v_mfma_f32_16x16x32_bf16 v[92:95], v[200:203], v[14:17], v[92:95]
	global_load_lds_dwordx4 v3, s[100:101] offset:3072
	v_mfma_f32_16x16x32_bf16 v[88:91], v[204:207], v[14:17], v[88:91]
	v_mfma_f32_16x16x32_bf16 v[68:71], v[192:195], v[18:21], v[68:71]
	s_add_u32 m0, m0, 0x1000
	v_mfma_f32_16x16x32_bf16 v[64:67], v[196:199], v[18:21], v[64:67]
	global_load_lds_dwordx4 v4, s[100:101]
	v_mfma_f32_16x16x32_bf16 v[60:63], v[200:203], v[18:21], v[60:63]
	v_mfma_f32_16x16x32_bf16 v[56:59], v[204:207], v[18:21], v[56:59]
	v_mfma_f32_16x16x32_bf16 v[36:39], v[192:195], v[152:155], v[36:39]
	global_load_lds_dwordx4 v5, s[100:101] offset:1024
	v_mfma_f32_16x16x32_bf16 v[32:35], v[196:199], v[152:155], v[32:35]
	v_mfma_f32_16x16x32_bf16 v[28:31], v[200:203], v[152:155], v[28:31]
	v_mfma_f32_16x16x32_bf16 v[24:27], v[204:207], v[152:155], v[24:27]
	s_add_u32 s98, s98, 64
	s_addc_u32 s99, s99, 0
	s_add_u32 s100, s100, 64
	s_addc_u32 s101, s101, 0
	s_add_u32 s9, s9, 0x6000
	s_cmp_eq_u32 s9, 0x12000
	s_cselect_b32 s9, 0, s9
	s_add_u32 s4, s4, 1
	s_branch .Lg162_end
.Lg162_sw:
	v_readlane_b32 vcc_lo, v253, 0
	v_readlane_b32 vcc_hi, v253, 1
	s_lshl_b32 s13, s7, 18
	s_nop 1
	s_add_u32 s98, vcc_lo, s13
	s_addc_u32 s99, vcc_hi, 0
	s_sub_u32 s98, s98, 0x1000
	s_subb_u32 s99, s99, 0
	v_readlane_b32 vcc_lo, v253, 2
	v_readlane_b32 vcc_hi, v253, 3
	s_lshl_b32 s13, s8, 19
	s_nop 1
	s_add_u32 s100, vcc_lo, s13
	s_addc_u32 s101, vcc_hi, 0
	s_sub_u32 s100, s100, 0x1000
	s_subb_u32 s101, s101, 0
	s_branch .Lg162_swret
.Lg162_end:
	v_writelane_b32 v253, s9, 4
	v_lshl_add_u32 v154, s6, 7, v168
	v_ashrrev_i32_e32 v155, 31, v154
	v_mov_b32_e32 v160, 1.0
	s_and_b64 vcc, exec, s[80:81]
	s_cbranch_vccz .LBB0_165
	v_lshl_add_u64 v[152:153], v[154:155], 2, s[70:71]
	global_load_dword v152, v[152:153], off
	s_waitcnt vmcnt(0)
	v_fmamk_f32 v152, v152, 0x3a800000, v212
	v_mul_f32_e32 v153, 0x4b800000, v152
	v_cmp_gt_f32_e32 vcc, s78, v152
	s_nop 1
	v_cndmask_b32_e32 v152, v152, v153, vcc
	v_rsq_f32_e32 v152, v152
	s_nop 0
	v_mul_f32_e32 v153, 0x45800000, v152
	v_cndmask_b32_e32 v160, v152, v153, vcc

; DI unsigned pk2(float lo, float hi) { f32x2 v = {lo, hi}; bf16x2_t r = __builtin_convertvector(v, bf16x2_t); return __builtin_bit_cast(unsigned, r); }
; DI f32x4 mfma(bf16x8 a, bf16x8 b, f32x4 c) { return __builtin_amdgcn_mfma_f32_16x16x32_bf16(a, b, c, 0, 0, 0); }
; DI void phase_compress(const Params& p, int l, char* smem) {
;     ...
; #pragma unroll 4
;         for (int ks = 0; ks < 64; ++ks) {
;             const int t = ks >> 1, db = (ks & 1) * 32 + fq * 8;
;             const u32x4 xv = *(const u32x4*)(xr + (size_t)t * DINP + db);
;             const f32x4 p0 = *(const f32x4*)(pos + t * 64 + db), p1 = *(const f32x4*)(pos + t * 64 + db + 4);
;             bf16x8 wf[4];
; #pragma unroll
;             for (int i = 0; i < 4; ++i) wf[i] = *(const bf16x8*)(w1 + (size_t)i * 16 * 2048 + ks * 32);
;             u32x4 xb;
;             xb[0] = pk2(__uint_as_float(xv[0] << 16) + p0[0], __uint_as_float(xv[0] & 0xffff0000u) + p0[1]);
;             xb[1] = pk2(__uint_as_float(xv[1] << 16) + p0[2], __uint_as_float(xv[1] & 0xffff0000u) + p0[3]);
;             xb[2] = pk2(__uint_as_float(xv[2] << 16) + p1[0], __uint_as_float(xv[2] & 0xffff0000u) + p1[1]);
;             xb[3] = pk2(__uint_as_float(xv[3] << 16) + p1[2], __uint_as_float(xv[3] & 0xffff0000u) + p1[3]);
;             const bf16x8 bx = __builtin_bit_cast(bf16x8, xb);
; #pragma unroll
;             for (int i = 0; i < 4; ++i) acc[i] = mfma(wf[i], bx, acc[i]);
;         }
.LBB0_357:
	v_lshl_add_u64 v[20:21], v[68:69], 0, v[46:47]
	s_mov_b64 s[24:25], 0x2000
	v_lshl_add_u64 v[28:29], v[70:71], 0, v[46:47]
	v_lshl_add_u64 v[36:37], v[66:67], 0, s[14:15]
	v_lshl_add_u64 v[22:23], v[20:21], 0, s[24:25]
	s_mov_b64 s[24:25], 0x10000
	v_lshl_add_u64 v[30:31], v[28:29], 0, s[24:25]
	v_lshl_add_u64 v[32:33], v[30:31], 0, s[24:25]
	v_lshl_add_u64 v[34:35], v[32:33], 0, s[24:25]
	global_load_dwordx4 v[24:27], v[20:21], off offset:3968
	global_load_dwordx4 v[38:41], v[36:37], off offset:16
	global_load_dwordx4 v[76:79], v[36:37], off
	global_load_dwordx4 v[80:83], v[28:29], off
	global_load_dwordx4 v[84:87], v[30:31], off
	global_load_dwordx4 v[88:91], v[32:33], off
	global_load_dwordx4 v[92:95], v[34:35], off
	global_load_dwordx4 v[96:99], v[20:21], off offset:4032
	global_load_dwordx4 v[104:107], v[36:37], off offset:144
	global_load_dwordx4 v[100:103], v[36:37], off offset:128
	global_load_dwordx4 v[108:111], v[28:29], off offset:64
	global_load_dwordx4 v[112:115], v[30:31], off offset:64
	global_load_dwordx4 v[116:119], v[32:33], off offset:64
	global_load_dwordx4 v[120:123], v[34:35], off offset:64
	global_load_dwordx4 v[124:127], v[22:23], off offset:1920
	global_load_dwordx4 v[132:135], v[36:37], off offset:272
	global_load_dwordx4 v[128:131], v[36:37], off offset:256
	global_load_dwordx4 v[136:139], v[28:29], off offset:128
	global_load_dwordx4 v[140:143], v[30:31], off offset:128
	global_load_dwordx4 v[144:147], v[32:33], off offset:128
	global_load_dwordx4 v[148:151], v[34:35], off offset:128
	global_load_dwordx4 v[152:155], v[22:23], off offset:1984
	global_load_dwordx4 v[160:163], v[36:37], off offset:400
	global_load_dwordx4 v[156:159], v[36:37], off offset:384
	global_load_dwordx4 v[164:167], v[28:29], off offset:192
	global_load_dwordx4 v[168:171], v[30:31], off offset:192
	global_load_dwordx4 v[172:175], v[32:33], off offset:192
	global_load_dwordx4 v[176:179], v[34:35], off offset:192
	s_mov_b64 s[24:25], 0x3000
	v_lshl_add_u64 v[20:21], v[20:21], 0, s[24:25]
	v_lshl_add_u64 v[22:23], v[22:23], 0, s[24:25]
	s_mov_b64 s[24:25], 0x100
	v_lshl_add_u64 v[28:29], v[28:29], 0, s[24:25]
	v_lshl_add_u64 v[30:31], v[30:31], 0, s[24:25]
	v_lshl_add_u64 v[32:33], v[32:33], 0, s[24:25]
	v_lshl_add_u64 v[34:35], v[34:35], 0, s[24:25]
	s_mov_b64 s[24:25], 0x200
	v_lshl_add_u64 v[36:37], v[36:37], 0, s[24:25]
	s_mov_b32 s14, 0
.Lcmp_loop:
	s_waitcnt vmcnt(21)
	v_lshlrev_b32_e32 v4, 16, v24
	v_and_b32_e32 v5, 0xffff0000, v24
	v_pk_add_f32 v[4:5], v[76:77], v[4:5]
	s_nop 0
	v_cvt_pk_bf16_f32 v24, v4, v5
	v_lshlrev_b32_e32 v6, 16, v25
	v_and_b32_e32 v7, 0xffff0000, v25
	v_pk_add_f32 v[6:7], v[78:79], v[6:7]
	s_nop 0
	v_cvt_pk_bf16_f32 v25, v6, v7
	v_lshlrev_b32_e32 v4, 16, v26
	v_and_b32_e32 v5, 0xffff0000, v26
	v_pk_add_f32 v[4:5], v[38:39], v[4:5]
	s_nop 0
	v_cvt_pk_bf16_f32 v26, v4, v5
	v_lshlrev_b32_e32 v6, 16, v27
	v_and_b32_e32 v7, 0xffff0000, v27
	v_pk_add_f32 v[6:7], v[40:41], v[6:7]
	s_nop 0
	v_cvt_pk_bf16_f32 v27, v6, v7
	s_nop 1
	v_mfma_f32_16x16x32_bf16 v[16:19], v[80:83], v[24:27], v[16:19]
	v_mfma_f32_16x16x32_bf16 v[0:3], v[84:87], v[24:27], v[0:3]
	v_mfma_f32_16x16x32_bf16 v[12:15], v[88:91], v[24:27], v[12:15]
	v_mfma_f32_16x16x32_bf16 v[8:11], v[92:95], v[24:27], v[8:11]
	global_load_dwordx4 v[24:27], v[20:21], off offset:3968
	global_load_dwordx4 v[38:41], v[36:37], off offset:16
	global_load_dwordx4 v[76:79], v[36:37], off
	global_load_dwordx4 v[80:83], v[28:29], off
	global_load_dwordx4 v[84:87], v[30:31], off
	global_load_dwordx4 v[88:91], v[32:33], off
	global_load_dwordx4 v[92:95], v[34:35], off
	s_waitcnt vmcnt(21)
	v_lshlrev_b32_e32 v4, 16, v96
	v_and_b32_e32 v5, 0xffff0000, v96
	v_pk_add_f32 v[4:5], v[100:101], v[4:5]
	s_nop 0
	v_cvt_pk_bf16_f32 v96, v4, v5
	v_lshlrev_b32_e32 v6, 16, v97
	v_and_b32_e32 v7, 0xffff0000, v97
	v_pk_add_f32 v[6:7], v[102:103], v[6:7]
	s_nop 0
	v_cvt_pk_bf16_f32 v97, v6, v7
	v_lshlrev_b32_e32 v4, 16, v98
	v_and_b32_e32 v5, 0xffff0000, v98
	v_pk_add_f32 v[4:5], v[104:105], v[4:5]
	s_nop 0
	v_cvt_pk_bf16_f32 v98, v4, v5
	v_lshlrev_b32_e32 v6, 16, v99
	v_and_b32_e32 v7, 0xffff0000, v99
	v_pk_add_f32 v[6:7], v[106:107], v[6:7]
	s_nop 0
	v_cvt_pk_bf16_f32 v99, v6, v7
	s_nop 1
	v_mfma_f32_16x16x32_bf16 v[16:19], v[108:111], v[96:99], v[16:19]
	v_mfma_f32_16x16x32_bf16 v[0:3], v[112:115], v[96:99], v[0:3]
	v_mfma_f32_16x16x32_bf16 v[12:15], v[116:119], v[96:99], v[12:15]
	v_mfma_f32_16x16x32_bf16 v[8:11], v[120:123], v[96:99], v[8:11]
	global_load_dwordx4 v[96:99], v[20:21], off offset:4032
	global_load_dwordx4 v[104:107], v[36:37], off offset:144
	global_load_dwordx4 v[100:103], v[36:37], off offset:128
	global_load_dwordx4 v[108:111], v[28:29], off offset:64
	global_load_dwordx4 v[112:115], v[30:31], off offset:64
	global_load_dwordx4 v[116:119], v[32:33], off offset:64
	global_load_dwordx4 v[120:123], v[34:35], off offset:64
	s_waitcnt vmcnt(21)
	v_lshlrev_b32_e32 v4, 16, v124
	v_and_b32_e32 v5, 0xffff0000, v124
	v_pk_add_f32 v[4:5], v[128:129], v[4:5]
	s_nop 0
	v_cvt_pk_bf16_f32 v124, v4, v5
	v_lshlrev_b32_e32 v6, 16, v125
	v_and_b32_e32 v7, 0xffff0000, v125
	v_pk_add_f32 v[6:7], v[130:131], v[6:7]
	s_nop 0
	v_cvt_pk_bf16_f32 v125, v6, v7
	v_lshlrev_b32_e32 v4, 16, v126
	v_and_b32_e32 v5, 0xffff0000, v126
	v_pk_add_f32 v[4:5], v[132:133], v[4:5]
	s_nop 0
	v_cvt_pk_bf16_f32 v126, v4, v5
	v_lshlrev_b32_e32 v6, 16, v127
	v_and_b32_e32 v7, 0xffff0000, v127
	v_pk_add_f32 v[6:7], v[134:135], v[6:7]
	s_nop 0
	v_cvt_pk_bf16_f32 v127, v6, v7
	s_nop 1
	v_mfma_f32_16x16x32_bf16 v[16:19], v[136:139], v[124:127], v[16:19]
	v_mfma_f32_16x16x32_bf16 v[0:3], v[140:143], v[124:127], v[0:3]
	v_mfma_f32_16x16x32_bf16 v[12:15], v[144:147], v[124:127], v[12:15]
	v_mfma_f32_16x16x32_bf16 v[8:11], v[148:151], v[124:127], v[8:11]
	global_load_dwordx4 v[124:127], v[22:23], off offset:1920
	global_load_dwordx4 v[132:135], v[36:37], off offset:272
	global_load_dwordx4 v[128:131], v[36:37], off offset:256
	global_load_dwordx4 v[136:139], v[28:29], off offset:128
	global_load_dwordx4 v[140:143], v[30:31], off offset:128
	global_load_dwordx4 v[144:147], v[32:33], off offset:128
	global_load_dwordx4 v[148:151], v[34:35], off offset:128
	s_waitcnt vmcnt(21)
; DI unsigned pk2(float lo, float hi) { f32x2 v = {lo, hi}; bf16x2_t r = __builtin_convertvector(v, bf16x2_t); return __builtin_bit_cast(unsigned, r); }
; DI f32x4 mfma(bf16x8 a, bf16x8 b, f32x4 c) { return __builtin_amdgcn_mfma_f32_16x16x32_bf16(a, b, c, 0, 0, 0); }
; DI void phase_compress(const Params& p, int l, char* smem) {
;     ...
; #pragma unroll 4
;         for (int ks = 0; ks < 64; ++ks) {
;             const int t = ks >> 1, db = (ks & 1) * 32 + fq * 8;
;             const u32x4 xv = *(const u32x4*)(xr + (size_t)t * DINP + db);
;             const f32x4 p0 = *(const f32x4*)(pos + t * 64 + db), p1 = *(const f32x4*)(pos + t * 64 + db + 4);
;             bf16x8 wf[4];
; #pragma unroll
;             for (int i = 0; i < 4; ++i) wf[i] = *(const bf16x8*)(w1 + (size_t)i * 16 * 2048 + ks * 32);
;             u32x4 xb;
;             xb[0] = pk2(__uint_as_float(xv[0] << 16) + p0[0], __uint_as_float(xv[0] & 0xffff0000u) + p0[1]);
;             xb[1] = pk2(__uint_as_float(xv[1] << 16) + p0[2], __uint_as_float(xv[1] & 0xffff0000u) + p0[3]);
;             xb[2] = pk2(__uint_as_float(xv[2] << 16) + p1[0], __uint_as_float(xv[2] & 0xffff0000u) + p1[1]);
;             xb[3] = pk2(__uint_as_float(xv[3] << 16) + p1[2], __uint_as_float(xv[3] & 0xffff0000u) + p1[3]);
;             const bf16x8 bx = __builtin_bit_cast(bf16x8, xb);
; #pragma unroll
;             for (int i = 0; i < 4; ++i) acc[i] = mfma(wf[i], bx, acc[i]);
;         }
	v_lshlrev_b32_e32 v4, 16, v152
	v_and_b32_e32 v5, 0xffff0000, v152
	v_pk_add_f32 v[4:5], v[156:157], v[4:5]
	s_nop 0
	v_cvt_pk_bf16_f32 v152, v4, v5
	v_lshlrev_b32_e32 v6, 16, v153
	v_and_b32_e32 v7, 0xffff0000, v153
	v_pk_add_f32 v[6:7], v[158:159], v[6:7]
	s_nop 0
	v_cvt_pk_bf16_f32 v153, v6, v7
	v_lshlrev_b32_e32 v4, 16, v154
	v_and_b32_e32 v5, 0xffff0000, v154
	v_pk_add_f32 v[4:5], v[160:161], v[4:5]
	s_nop 0
	v_cvt_pk_bf16_f32 v154, v4, v5
	v_lshlrev_b32_e32 v6, 16, v155
	v_and_b32_e32 v7, 0xffff0000, v155
	v_pk_add_f32 v[6:7], v[162:163], v[6:7]
	s_nop 0
	v_cvt_pk_bf16_f32 v155, v6, v7
	s_nop 1
	v_mfma_f32_16x16x32_bf16 v[16:19], v[164:167], v[152:155], v[16:19]
	v_mfma_f32_16x16x32_bf16 v[0:3], v[168:171], v[152:155], v[0:3]
	v_mfma_f32_16x16x32_bf16 v[12:15], v[172:175], v[152:155], v[12:15]
	v_mfma_f32_16x16x32_bf16 v[8:11], v[176:179], v[152:155], v[8:11]
	global_load_dwordx4 v[152:155], v[22:23], off offset:1984
	global_load_dwordx4 v[160:163], v[36:37], off offset:400
	global_load_dwordx4 v[156:159], v[36:37], off offset:384
	global_load_dwordx4 v[164:167], v[28:29], off offset:192
	global_load_dwordx4 v[168:171], v[30:31], off offset:192
	global_load_dwordx4 v[172:175], v[32:33], off offset:192
	global_load_dwordx4 v[176:179], v[34:35], off offset:192
	s_mov_b64 s[24:25], 0x3000
	v_lshl_add_u64 v[20:21], v[20:21], 0, s[24:25]
	v_lshl_add_u64 v[22:23], v[22:23], 0, s[24:25]
	s_mov_b64 s[24:25], 0x100
	v_lshl_add_u64 v[28:29], v[28:29], 0, s[24:25]
	v_lshl_add_u64 v[30:31], v[30:31], 0, s[24:25]
	v_lshl_add_u64 v[32:33], v[32:33], 0, s[24:25]
	v_lshl_add_u64 v[34:35], v[34:35], 0, s[24:25]
	s_mov_b64 s[24:25], 0x200
	v_lshl_add_u64 v[36:37], v[36:37], 0, s[24:25]
	s_add_i32 s14, s14, 1
	s_cmp_lt_u32 s14, 15
	s_cbranch_scc1 .Lcmp_loop
	s_waitcnt vmcnt(21)
	v_lshlrev_b32_e32 v4, 16, v24
	v_and_b32_e32 v5, 0xffff0000, v24
	v_pk_add_f32 v[4:5], v[76:77], v[4:5]
	s_nop 0
	v_cvt_pk_bf16_f32 v24, v4, v5
	v_lshlrev_b32_e32 v6, 16, v25
	v_and_b32_e32 v7, 0xffff0000, v25
	v_pk_add_f32 v[6:7], v[78:79], v[6:7]
	s_nop 0
	v_cvt_pk_bf16_f32 v25, v6, v7
	v_lshlrev_b32_e32 v4, 16, v26
	v_and_b32_e32 v5, 0xffff0000, v26
	v_pk_add_f32 v[4:5], v[38:39], v[4:5]
	s_nop 0
	v_cvt_pk_bf16_f32 v26, v4, v5
	v_lshlrev_b32_e32 v6, 16, v27
	v_and_b32_e32 v7, 0xffff0000, v27
	v_pk_add_f32 v[6:7], v[40:41], v[6:7]
	s_nop 0
	v_cvt_pk_bf16_f32 v27, v6, v7
	s_nop 1
	v_mfma_f32_16x16x32_bf16 v[16:19], v[80:83], v[24:27], v[16:19]
	v_mfma_f32_16x16x32_bf16 v[0:3], v[84:87], v[24:27], v[0:3]
	v_mfma_f32_16x16x32_bf16 v[12:15], v[88:91], v[24:27], v[12:15]
	v_mfma_f32_16x16x32_bf16 v[8:11], v[92:95], v[24:27], v[8:11]
	s_waitcnt vmcnt(14)
	v_lshlrev_b32_e32 v4, 16, v96
	v_and_b32_e32 v5, 0xffff0000, v96
	v_pk_add_f32 v[4:5], v[100:101], v[4:5]
	s_nop 0
	v_cvt_pk_bf16_f32 v96, v4, v5
	v_lshlrev_b32_e32 v6, 16, v97
	v_and_b32_e32 v7, 0xffff0000, v97
	v_pk_add_f32 v[6:7], v[102:103], v[6:7]
	s_nop 0
	v_cvt_pk_bf16_f32 v97, v6, v7
	v_lshlrev_b32_e32 v4, 16, v98
	v_and_b32_e32 v5, 0xffff0000, v98
	v_pk_add_f32 v[4:5], v[104:105], v[4:5]
	s_nop 0
	v_cvt_pk_bf16_f32 v98, v4, v5
	v_lshlrev_b32_e32 v6, 16, v99
	v_and_b32_e32 v7, 0xffff0000, v99
	v_pk_add_f32 v[6:7], v[106:107], v[6:7]
	s_nop 0
	v_cvt_pk_bf16_f32 v99, v6, v7
	s_nop 1
	v_mfma_f32_16x16x32_bf16 v[16:19], v[108:111], v[96:99], v[16:19]
	v_mfma_f32_16x16x32_bf16 v[0:3], v[112:115], v[96:99], v[0:3]
	v_mfma_f32_16x16x32_bf16 v[12:15], v[116:119], v[96:99], v[12:15]
	v_mfma_f32_16x16x32_bf16 v[8:11], v[120:123], v[96:99], v[8:11]
	s_waitcnt vmcnt(7)
	v_lshlrev_b32_e32 v4, 16, v124
	v_and_b32_e32 v5, 0xffff0000, v124
	v_pk_add_f32 v[4:5], v[128:129], v[4:5]
	s_nop 0
	v_cvt_pk_bf16_f32 v124, v4, v5
	v_lshlrev_b32_e32 v6, 16, v125
	v_and_b32_e32 v7, 0xffff0000, v125
	v_pk_add_f32 v[6:7], v[130:131], v[6:7]
	s_nop 0
	v_cvt_pk_bf16_f32 v125, v6, v7
	v_lshlrev_b32_e32 v4, 16, v126
	v_and_b32_e32 v5, 0xffff0000, v126
	v_pk_add_f32 v[4:5], v[132:133], v[4:5]
	s_nop 0
	v_cvt_pk_bf16_f32 v126, v4, v5
	v_lshlrev_b32_e32 v6, 16, v127
	v_and_b32_e32 v7, 0xffff0000, v127
	v_pk_add_f32 v[6:7], v[134:135], v[6:7]
	s_nop 0
	v_cvt_pk_bf16_f32 v127, v6, v7
	s_nop 1
	v_mfma_f32_16x16x32_bf16 v[16:19], v[136:139], v[124:127], v[16:19]
	v_mfma_f32_16x16x32_bf16 v[0:3], v[140:143], v[124:127], v[0:3]
	v_mfma_f32_16x16x32_bf16 v[12:15], v[144:147], v[124:127], v[12:15]
	v_mfma_f32_16x16x32_bf16 v[8:11], v[148:151], v[124:127], v[8:11]
	s_waitcnt vmcnt(0)
; DI unsigned pk2(float lo, float hi) { f32x2 v = {lo, hi}; bf16x2_t r = __builtin_convertvector(v, bf16x2_t); return __builtin_bit_cast(unsigned, r); }
; DI f32x4 mfma(bf16x8 a, bf16x8 b, f32x4 c) { return __builtin_amdgcn_mfma_f32_16x16x32_bf16(a, b, c, 0, 0, 0); }
; DI float siluf_(float x) { return x / (1.f + __expf(-x)); }
; DI void phase_compress(const Params& p, int l, char* smem) {
;     ...
; #pragma unroll 4
;         for (int ks = 0; ks < 64; ++ks) {
;             const int t = ks >> 1, db = (ks & 1) * 32 + fq * 8;
;             const u32x4 xv = *(const u32x4*)(xr + (size_t)t * DINP + db);
;             const f32x4 p0 = *(const f32x4*)(pos + t * 64 + db), p1 = *(const f32x4*)(pos + t * 64 + db + 4);
;             bf16x8 wf[4];
; #pragma unroll
;             for (int i = 0; i < 4; ++i) wf[i] = *(const bf16x8*)(w1 + (size_t)i * 16 * 2048 + ks * 32);
;             u32x4 xb;
;             xb[0] = pk2(__uint_as_float(xv[0] << 16) + p0[0], __uint_as_float(xv[0] & 0xffff0000u) + p0[1]);
;             xb[1] = pk2(__uint_as_float(xv[1] << 16) + p0[2], __uint_as_float(xv[1] & 0xffff0000u) + p0[3]);
;             xb[2] = pk2(__uint_as_float(xv[2] << 16) + p1[0], __uint_as_float(xv[2] & 0xffff0000u) + p1[1]);
;             xb[3] = pk2(__uint_as_float(xv[3] << 16) + p1[2], __uint_as_float(xv[3] & 0xffff0000u) + p1[3]);
;             const bf16x8 bx = __builtin_bit_cast(bf16x8, xb);
; #pragma unroll
;             for (int i = 0; i < 4; ++i) acc[i] = mfma(wf[i], bx, acc[i]);
;         }
;         f32x4 o[4];
; #pragma unroll
;         for (int i = 0; i < 4; ++i) o[i] = (f32x4){0.f, 0.f, 0.f, 0.f};
; #pragma unroll
;         for (int kk = 0; kk < 2; ++kk) {
;             const int k2 = wave * 2 + kk;
;             f32x4 a = acc[2 * kk], c2 = acc[2 * kk + 1];
; #pragma unroll
;             for (int e = 0; e < 4; ++e) { a[e] = siluf_(a[e]); c2[e] = siluf_(c2[e]); }
;             const bf16x8 hb = pack2(a, c2);
; #pragma unroll
;             for (int t2 = 0; t2 < 4; ++t2) {
;                 const bf16_t* wr = w2 + (size_t)(t2 * 16 + fr) * 256 + k2 * 32 + fq * 4;
;                 const u32x2 lo = *(const u32x2*)wr, hi = *(const u32x2*)(wr + 16);
;                 u32x4 wv; wv[0] = lo[0]; wv[1] = lo[1]; wv[2] = hi[0]; wv[3] = hi[1];
;                 o[t2] = mfma(__builtin_bit_cast(bf16x8, wv), hb, o[t2]);
	v_lshlrev_b32_e32 v4, 16, v152
	v_and_b32_e32 v5, 0xffff0000, v152
	v_pk_add_f32 v[4:5], v[156:157], v[4:5]
	s_nop 0
	v_cvt_pk_bf16_f32 v152, v4, v5
	v_lshlrev_b32_e32 v6, 16, v153
	v_and_b32_e32 v7, 0xffff0000, v153
	v_pk_add_f32 v[6:7], v[158:159], v[6:7]
	s_nop 0
	v_cvt_pk_bf16_f32 v153, v6, v7
	v_lshlrev_b32_e32 v4, 16, v154
	v_and_b32_e32 v5, 0xffff0000, v154
	v_pk_add_f32 v[4:5], v[160:161], v[4:5]
	s_nop 0
	v_cvt_pk_bf16_f32 v154, v4, v5
	v_lshlrev_b32_e32 v6, 16, v155
	v_and_b32_e32 v7, 0xffff0000, v155
	v_pk_add_f32 v[6:7], v[162:163], v[6:7]
	s_nop 0
	v_cvt_pk_bf16_f32 v155, v6, v7
	s_nop 1
	v_mfma_f32_16x16x32_bf16 v[16:19], v[164:167], v[152:155], v[16:19]
	v_mfma_f32_16x16x32_bf16 v[0:3], v[168:171], v[152:155], v[0:3]
	v_mfma_f32_16x16x32_bf16 v[12:15], v[172:175], v[152:155], v[12:15]
	v_mfma_f32_16x16x32_bf16 v[8:11], v[176:179], v[152:155], v[8:11]
	s_nop 7
	s_nop 2
	v_mul_f32_e32 v5, 0xbfb8aa3b, v0
	v_mul_f32_e32 v4, 0xbfb8aa3b, v16
	v_exp_f32_e32 v6, v5
	v_mul_f32_e32 v5, 0xbfb8aa3b, v17
	v_exp_f32_e32 v4, v4
	v_exp_f32_e32 v5, v5
	s_lshl_b64 s[10:11], s[10:11], 15
	v_lshl_add_u64 v[24:25], v[44:45], 0, s[10:11]
	v_mov_b32_e32 v57, v189
	v_pk_add_f32 v[4:5], v[4:5], 1.0 op_sel_hi:[1,0]
	v_lshl_add_u64 v[26:27], v[24:25], 0, v[56:57]
	v_div_scale_f32 v7, s[14:15], v5, v5, v17
	v_rcp_f32_e32 v20, v7
	v_mov_b32_e32 v59, v189
	v_mov_b32_e32 v61, v189
	v_mov_b32_e32 v63, v189
	v_fma_f32 v21, -v7, v20, 1.0
	v_fmac_f32_e32 v20, v21, v20
	v_div_scale_f32 v21, vcc, v17, v5, v17
	v_mul_f32_e32 v22, v21, v20
	v_fma_f32 v23, -v7, v22, v21
	v_fmac_f32_e32 v22, v23, v20
	v_fma_f32 v7, -v7, v22, v21
	v_div_fmas_f32 v7, v7, v20, v22
	v_div_fixup_f32 v17, v7, v5, v17
	v_div_scale_f32 v5, s[14:15], v4, v4, v16
	v_rcp_f32_e32 v7, v5
	v_lshl_add_u64 v[30:31], v[24:25], 0, v[62:63]
	v_fma_f32 v20, -v5, v7, 1.0
	v_fmac_f32_e32 v7, v20, v7
	v_div_scale_f32 v20, vcc, v16, v4, v16
	v_mul_f32_e32 v21, v20, v7
	v_fma_f32 v22, -v5, v21, v20
	v_fmac_f32_e32 v21, v22, v7
	v_fma_f32 v5, -v5, v21, v20
	v_div_fmas_f32 v5, v5, v7, v21
	v_div_fixup_f32 v16, v5, v4, v16
	v_mul_f32_e32 v4, 0xbfb8aa3b, v1
	v_exp_f32_e32 v7, v4
	s_nop 0
	v_pk_add_f32 v[4:5], v[6:7], 1.0 op_sel_hi:[1,0]
	s_nop 0
	v_div_scale_f32 v6, s[14:15], v5, v5, v1
	v_rcp_f32_e32 v7, v6
	s_nop 0
	v_fma_f32 v20, -v6, v7, 1.0
	v_fmac_f32_e32 v7, v20, v7
	v_div_scale_f32 v20, vcc, v1, v5, v1
	v_mul_f32_e32 v21, v20, v7
	v_fma_f32 v22, -v6, v21, v20
	v_fmac_f32_e32 v21, v22, v7
	v_fma_f32 v6, -v6, v21, v20
	v_div_fmas_f32 v6, v6, v7, v21
	v_div_fixup_f32 v6, v6, v5, v1
	v_div_scale_f32 v1, s[14:15], v4, v4, v0
	v_rcp_f32_e32 v5, v1
	s_nop 0
	v_fma_f32 v7, -v1, v5, 1.0
	v_fmac_f32_e32 v5, v7, v5
	v_div_scale_f32 v7, vcc, v0, v4, v0
	v_mul_f32_e32 v20, v7, v5
	v_fma_f32 v21, -v1, v20, v7
	v_fmac_f32_e32 v20, v21, v5
	v_fma_f32 v1, -v1, v20, v7
	v_div_fmas_f32 v1, v1, v5, v20
	v_div_fixup_f32 v7, v1, v4, v0
	v_mul_f32_e32 v1, 0xbfb8aa3b, v2
	v_mul_f32_e32 v0, 0xbfb8aa3b, v18
	v_exp_f32_e32 v4, v1
	v_mul_f32_e32 v1, 0xbfb8aa3b, v19
	v_exp_f32_e32 v0, v0
	v_exp_f32_e32 v1, v1
	s_nop 0
	v_pk_add_f32 v[0:1], v[0:1], 1.0 op_sel_hi:[1,0]
	s_nop 0
	v_div_scale_f32 v5, s[14:15], v1, v1, v19
	v_rcp_f32_e32 v20, v5
	s_nop 0
	v_fma_f32 v21, -v5, v20, 1.0
	v_fmac_f32_e32 v20, v21, v20
	v_div_scale_f32 v21, vcc, v19, v1, v19
	v_mul_f32_e32 v22, v21, v20
	v_fma_f32 v23, -v5, v22, v21
	v_fmac_f32_e32 v22, v23, v20
	v_fma_f32 v5, -v5, v22, v21
	v_div_fmas_f32 v5, v5, v20, v22
	v_div_fixup_f32 v19, v5, v1, v19
	v_div_scale_f32 v1, s[14:15], v0, v0, v18
	v_rcp_f32_e32 v5, v1
	s_nop 0
	v_fma_f32 v20, -v1, v5, 1.0
	v_fmac_f32_e32 v5, v20, v5
	v_div_scale_f32 v20, vcc, v18, v0, v18
	v_mul_f32_e32 v21, v20, v5
	v_fma_f32 v22, -v1, v21, v20
	v_fmac_f32_e32 v21, v22, v5
	v_fma_f32 v1, -v1, v21, v20
	v_div_fmas_f32 v1, v1, v5, v21
	v_div_fixup_f32 v18, v1, v0, v18
	v_mul_f32_e32 v0, 0xbfb8aa3b, v3
	v_exp_f32_e32 v5, v0
	s_nop 0
	v_pk_add_f32 v[0:1], v[4:5], 1.0 op_sel_hi:[1,0]
	s_nop 0
	v_div_scale_f32 v4, s[14:15], v1, v1, v3
	v_rcp_f32_e32 v5, v4
	s_nop 0
	v_fma_f32 v20, -v4, v5, 1.0
	v_fmac_f32_e32 v5, v20, v5
	v_div_scale_f32 v20, vcc, v3, v1, v3
	v_mul_f32_e32 v21, v20, v5
	v_fma_f32 v22, -v4, v21, v20
	v_fmac_f32_e32 v21, v22, v5
	v_fma_f32 v4, -v4, v21, v20
	v_div_fmas_f32 v4, v4, v5, v21
	v_div_fixup_f32 v3, v4, v1, v3
	v_div_scale_f32 v1, s[14:15], v0, v0, v2
	v_rcp_f32_e32 v4, v1
	s_nop 0
	v_fma_f32 v5, -v1, v4, 1.0
	v_fmac_f32_e32 v4, v5, v4
	v_div_scale_f32 v5, vcc, v2, v0, v2
	v_mul_f32_e32 v20, v5, v4
	v_fma_f32 v21, -v1, v20, v5
	v_fmac_f32_e32 v20, v21, v4
	v_fma_f32 v1, -v1, v20, v5
	v_div_fmas_f32 v1, v1, v4, v20
	v_div_fixup_f32 v4, v1, v0, v2
	v_cvt_pk_bf16_f32 v2, v7, v6
	v_cvt_pk_bf16_f32 v3, v4, v3
	global_load_dwordx2 v[4:5], v[26:27], off
	global_load_dwordx2 v[6:7], v[26:27], off offset:32
	v_cvt_pk_bf16_f32 v0, v16, v17
	v_cvt_pk_bf16_f32 v1, v18, v19
	s_waitcnt vmcnt(0)
	s_nop 0
	v_mfma_f32_16x16x32_bf16 v[16:19], v[4:7], v[0:3], 0
	v_lshl_add_u64 v[6:7], v[24:25], 0, v[58:59]
	global_load_dwordx2 v[4:5], v[6:7], off
	s_nop 0
	global_load_dwordx2 v[6:7], v[6:7], off offset:32
	s_waitcnt vmcnt(0)
	v_mfma_f32_16x16x32_bf16 v[20:23], v[4:7], v[0:3], 0
	v_lshl_add_u64 v[6:7], v[24:25], 0, v[60:61]
	global_load_dwordx2 v[4:5], v[6:7], off
	s_nop 0
	global_load_dwordx2 v[6:7], v[6:7], off offset:32
	s_nop 0
	global_load_dwordx2 v[28:29], v[30:31], off
	s_nop 0
	global_load_dwordx2 v[30:31], v[30:31], off offset:32
	v_lshl_add_u64 v[24:25], v[24:25], 0, 64
	s_waitcnt vmcnt(2)
	v_mfma_f32_16x16x32_bf16 v[4:7], v[4:7], v[0:3], 0
	s_waitcnt vmcnt(0)
; DI f32x4 mfma(bf16x8 a, bf16x8 b, f32x4 c) { return __builtin_amdgcn_mfma_f32_16x16x32_bf16(a, b, c, 0, 0, 0); }
; DI float siluf_(float x) { return x / (1.f + __expf(-x)); }
; DI void phase_compress(const Params& p, int l, char* smem) {
;     ...
;         for (int kk = 0; kk < 2; ++kk) {
;             const int k2 = wave * 2 + kk;
;             f32x4 a = acc[2 * kk], c2 = acc[2 * kk + 1];
; #pragma unroll
;             for (int e = 0; e < 4; ++e) { a[e] = siluf_(a[e]); c2[e] = siluf_(c2[e]); }
;             const bf16x8 hb = pack2(a, c2);
; #pragma unroll
;             for (int t2 = 0; t2 < 4; ++t2) {
;                 const bf16_t* wr = w2 + (size_t)(t2 * 16 + fr) * 256 + k2 * 32 + fq * 4;
;                 const u32x2 lo = *(const u32x2*)wr, hi = *(const u32x2*)(wr + 16);
;                 u32x4 wv; wv[0] = lo[0]; wv[1] = lo[1]; wv[2] = hi[0]; wv[3] = hi[1];
;                 o[t2] = mfma(__builtin_bit_cast(bf16x8, wv), hb, o[t2]);
;             }
;         }
; #pragma unroll
;         for (int t2 = 0; t2 < 4; ++t2)
; #pragma unroll
;             for (int e = 0; e < 4; ++e) red[(wave * 16 + t2 * 4 + e) * 64 + lane] = o[t2][e];
;         __syncthreads();
	v_mfma_f32_16x16x32_bf16 v[0:3], v[28:31], v[0:3], 0
	v_mul_f32_e32 v29, 0xbfb8aa3b, v8
	v_mul_f32_e32 v28, 0xbfb8aa3b, v12
	v_exp_f32_e32 v30, v29
	v_mul_f32_e32 v29, 0xbfb8aa3b, v13
	v_exp_f32_e32 v28, v28
	v_exp_f32_e32 v29, v29
	s_nop 0
	v_pk_add_f32 v[28:29], v[28:29], 1.0 op_sel_hi:[1,0]
	s_nop 0
	v_div_scale_f32 v31, s[10:11], v29, v29, v13
	v_rcp_f32_e32 v32, v31
	s_nop 0
	v_fma_f32 v33, -v31, v32, 1.0
	v_fmac_f32_e32 v32, v33, v32
	v_div_scale_f32 v33, vcc, v13, v29, v13
	v_mul_f32_e32 v34, v33, v32
	v_fma_f32 v35, -v31, v34, v33
	v_fmac_f32_e32 v34, v35, v32
	v_fma_f32 v31, -v31, v34, v33
	v_div_fmas_f32 v31, v31, v32, v34
	v_div_fixup_f32 v29, v31, v29, v13
	v_div_scale_f32 v13, s[10:11], v28, v28, v12
	v_rcp_f32_e32 v31, v13
	s_nop 0
	v_fma_f32 v32, -v13, v31, 1.0
	v_fmac_f32_e32 v31, v32, v31
	v_div_scale_f32 v32, vcc, v12, v28, v12
	v_mul_f32_e32 v33, v32, v31
	v_fma_f32 v34, -v13, v33, v32
	v_fmac_f32_e32 v33, v34, v31
	v_fma_f32 v13, -v13, v33, v32
	v_div_fmas_f32 v13, v13, v31, v33
	v_div_fixup_f32 v28, v13, v28, v12
	v_mul_f32_e32 v12, 0xbfb8aa3b, v9
	v_exp_f32_e32 v31, v12
	s_nop 0
	v_pk_add_f32 v[12:13], v[30:31], 1.0 op_sel_hi:[1,0]
	s_nop 0
	v_div_scale_f32 v30, s[10:11], v13, v13, v9
	v_rcp_f32_e32 v31, v30
	s_nop 0
	v_fma_f32 v32, -v30, v31, 1.0
	v_fmac_f32_e32 v31, v32, v31
	v_div_scale_f32 v32, vcc, v9, v13, v9
	v_mul_f32_e32 v33, v32, v31
	v_fma_f32 v34, -v30, v33, v32
	v_fmac_f32_e32 v33, v34, v31
	v_fma_f32 v30, -v30, v33, v32
	v_div_fmas_f32 v30, v30, v31, v33
	v_div_fixup_f32 v30, v30, v13, v9
	v_div_scale_f32 v9, s[10:11], v12, v12, v8
	v_rcp_f32_e32 v13, v9
	s_nop 0
	v_fma_f32 v31, -v9, v13, 1.0
	v_fmac_f32_e32 v13, v31, v13
	v_div_scale_f32 v31, vcc, v8, v12, v8
	v_mul_f32_e32 v32, v31, v13
	v_fma_f32 v33, -v9, v32, v31
	v_fmac_f32_e32 v32, v33, v13
	v_fma_f32 v9, -v9, v32, v31
	v_div_fmas_f32 v9, v9, v13, v32
	v_div_fixup_f32 v31, v9, v12, v8
	v_mul_f32_e32 v9, 0xbfb8aa3b, v10
	v_mul_f32_e32 v8, 0xbfb8aa3b, v14
	v_exp_f32_e32 v12, v9
	v_mul_f32_e32 v9, 0xbfb8aa3b, v15
	v_exp_f32_e32 v8, v8
	v_exp_f32_e32 v9, v9
	s_nop 0
	v_pk_add_f32 v[8:9], v[8:9], 1.0 op_sel_hi:[1,0]
	s_nop 0
	v_div_scale_f32 v13, s[10:11], v9, v9, v15
	v_rcp_f32_e32 v32, v13
	s_nop 0
	v_fma_f32 v33, -v13, v32, 1.0
	v_fmac_f32_e32 v32, v33, v32
	v_div_scale_f32 v33, vcc, v15, v9, v15
	v_mul_f32_e32 v34, v33, v32
	v_fma_f32 v35, -v13, v34, v33
	v_fmac_f32_e32 v34, v35, v32
	v_fma_f32 v13, -v13, v34, v33
	v_div_fmas_f32 v13, v13, v32, v34
	v_div_fixup_f32 v15, v13, v9, v15
	v_div_scale_f32 v9, s[10:11], v8, v8, v14
	v_rcp_f32_e32 v13, v9
	s_nop 0
	v_fma_f32 v32, -v9, v13, 1.0
	v_fmac_f32_e32 v13, v32, v13
	v_div_scale_f32 v32, vcc, v14, v8, v14
	v_mul_f32_e32 v33, v32, v13
	v_fma_f32 v34, -v9, v33, v32
	v_fmac_f32_e32 v33, v34, v13
	v_fma_f32 v9, -v9, v33, v32
	v_div_fmas_f32 v9, v9, v13, v33
	v_div_fixup_f32 v14, v9, v8, v14
	v_mul_f32_e32 v8, 0xbfb8aa3b, v11
	v_exp_f32_e32 v13, v8
	s_nop 0
	v_pk_add_f32 v[8:9], v[12:13], 1.0 op_sel_hi:[1,0]
	s_nop 0
	v_div_scale_f32 v12, s[10:11], v9, v9, v11
	v_rcp_f32_e32 v13, v12
	s_nop 0
	v_fma_f32 v32, -v12, v13, 1.0
	v_fmac_f32_e32 v13, v32, v13
	v_div_scale_f32 v32, vcc, v11, v9, v11
	v_mul_f32_e32 v33, v32, v13
	v_fma_f32 v34, -v12, v33, v32
	v_fmac_f32_e32 v33, v34, v13
	v_fma_f32 v12, -v12, v33, v32
	v_div_fmas_f32 v12, v12, v13, v33
	v_div_fixup_f32 v11, v12, v9, v11
	v_div_scale_f32 v9, s[10:11], v8, v8, v10
	v_rcp_f32_e32 v12, v9
	s_nop 0
	v_fma_f32 v13, -v9, v12, 1.0
	v_fmac_f32_e32 v12, v13, v12
	v_div_scale_f32 v13, vcc, v10, v8, v10
	v_mul_f32_e32 v32, v13, v12
	v_fma_f32 v33, -v9, v32, v13
	v_fmac_f32_e32 v32, v33, v12
	v_fma_f32 v9, -v9, v32, v13
	v_div_fmas_f32 v9, v9, v12, v32
	v_div_fixup_f32 v12, v9, v8, v10
	v_cvt_pk_bf16_f32 v9, v14, v15
	v_cvt_pk_bf16_f32 v11, v12, v11
	global_load_dwordx2 v[12:13], v[26:27], off offset:64
	global_load_dwordx2 v[14:15], v[26:27], off offset:96
	v_cvt_pk_bf16_f32 v8, v28, v29
	v_cvt_pk_bf16_f32 v10, v31, v30
	s_and_b64 vcc, exec, s[8:9]
	s_waitcnt vmcnt(0)
	v_mfma_f32_16x16x32_bf16 v[12:15], v[12:15], v[8:11], v[16:19]
	s_nop 2
	v_lshl_add_u64 v[18:19], v[24:25], 0, v[58:59]
	global_load_dwordx2 v[16:17], v[18:19], off
	s_nop 0
	global_load_dwordx2 v[18:19], v[18:19], off offset:32
	s_waitcnt vmcnt(0)
	v_mfma_f32_16x16x32_bf16 v[16:19], v[16:19], v[8:11], v[20:23]
	s_nop 2
	v_lshl_add_u64 v[22:23], v[24:25], 0, v[60:61]
	global_load_dwordx2 v[20:21], v[22:23], off
	s_nop 0
	global_load_dwordx2 v[22:23], v[22:23], off offset:32
	s_waitcnt vmcnt(0)
	v_mfma_f32_16x16x32_bf16 v[4:7], v[20:23], v[8:11], v[4:7]
	v_lshl_add_u64 v[22:23], v[24:25], 0, v[62:63]
	global_load_dwordx2 v[20:21], v[22:23], off
	s_nop 0
	global_load_dwordx2 v[22:23], v[22:23], off offset:32
	s_waitcnt vmcnt(0)
	v_mfma_f32_16x16x32_bf16 v[0:3], v[20:23], v[8:11], v[0:3]
	v_add_u32_e32 v8, s17, v73
	ds_write2st64_b32 v8, v12, v13 offset1:1
	ds_write2st64_b32 v8, v14, v15 offset0:2 offset1:3
	ds_write2st64_b32 v8, v16, v17 offset0:4 offset1:5
	ds_write2st64_b32 v8, v18, v19 offset0:6 offset1:7
	ds_write2st64_b32 v8, v4, v5 offset0:8 offset1:9
	ds_write2st64_b32 v8, v6, v7 offset0:10 offset1:11
	s_nop 0
	ds_write2st64_b32 v8, v0, v1 offset0:12 offset1:13
	ds_write2st64_b32 v8, v2, v3 offset0:14 offset1:15
	s_waitcnt lgkmcnt(0)
	s_barrier
	s_cbranch_vccz .LBB0_355
; DI bf16_t f2bf(float x) { unsigned u = __float_as_uint(x); u += 0x7fffu + ((u >> 16) & 1u); return (bf16_t)(u >> 16); }
; DI unsigned pk2(float lo, float hi) { f32x2 v = {lo, hi}; bf16x2_t r = __builtin_convertvector(v, bf16x2_t); return __builtin_bit_cast(unsigned, r); }
; DI int PINV(int s) { return (s & ~31) | ((s & 12) << 1) | ((s & 16) >> 2) | (s & 3); }
; DI void phase_compress(const Params& p, int l, char* smem) {
;     ...
;         if (wave == 0) {
; #pragma unroll
;             for (int t2 = 0; t2 < 4; ++t2)
; #pragma unroll
;                 for (int e = 0; e < 4; ++e) o[t2][e] += red[(16 + t2 * 4 + e) * 64 + lane] + red[(32 + t2 * 4 + e) * 64 + lane] + red[(48 + t2 * 4 + e) * 64 + lane];
;             if (kv == 0) {
;                 float ss = 0.f;
; #pragma unroll
;                 for (int t2 = 0; t2 < 4; ++t2)
; #pragma unroll
;                     for (int e = 0; e < 4; ++e) ss += o[t2][e] * o[t2][e];
;                 ss += __shfl_xor(ss, 16); ss += __shfl_xor(ss, 32);
;                 const float r = (c <= 1022) ? rsqrtf(ss * (1.f / 64.f) + 1e-6f) : 0.f;
;                 const float* g = p.k_norm + (l * 3 + 0) * 64;
; #pragma unroll
;                 for (int t2 = 0; t2 < 4; ++t2) {
;                     const int n2 = t2 * 16 + fq * 4;
;                     u32x2 o2; o2[0] = pk2(o[t2][0] * r * g[n2], o[t2][1] * r * g[n2 + 1]); o2[1] = pk2(o[t2][2] * r * g[n2 + 2], o[t2][3] * r * g[n2 + 3]);
;                     *(u32x2*)(p.kc + (((size_t)(b * 2 + kvh) * 1024) + c) * 64 + n2) = o2;
;                 }
;             } else {
;                 const float z = (c <= 1022) ? 1.f : 0.f;
;                 bf16_t* dst = p.vct + ((size_t)(b * 2 + kvh) * 16 + (c >> 6)) * 4096 + PINV(c & 63);
; #pragma unroll
;                 for (int t2 = 0; t2 < 4; ++t2)
; #pragma unroll
;                     for (int e = 0; e < 4; ++e) dst[(t2 * 16 + fq * 4 + e) * 64] = f2bf(o[t2][e] * z);
;             }
	ds_read2st64_b32 v[8:9], v73 offset0:16 offset1:17
	ds_read2st64_b32 v[10:11], v73 offset0:32 offset1:33
	ds_read2st64_b32 v[20:21], v73 offset0:48 offset1:49
	s_and_b32 s14, s22, 1
	s_mov_b64 s[10:11], -1
	s_cmpk_gt_u32 s13, 0xff
	s_waitcnt lgkmcnt(1)
	v_pk_add_f32 v[8:9], v[8:9], v[10:11]
	s_waitcnt lgkmcnt(0)
	v_pk_add_f32 v[8:9], v[8:9], v[20:21]
	s_nop 0
	v_pk_add_f32 v[12:13], v[12:13], v[8:9]
	ds_read2st64_b32 v[8:9], v73 offset0:18 offset1:19
	ds_read2st64_b32 v[10:11], v73 offset0:34 offset1:35
	ds_read2st64_b32 v[20:21], v73 offset0:50 offset1:51
	s_waitcnt lgkmcnt(1)
	v_pk_add_f32 v[8:9], v[8:9], v[10:11]
	s_waitcnt lgkmcnt(0)
	v_pk_add_f32 v[8:9], v[8:9], v[20:21]
	s_nop 0
	v_pk_add_f32 v[10:11], v[14:15], v[8:9]
	ds_read2st64_b32 v[8:9], v73 offset0:20 offset1:21
	ds_read2st64_b32 v[14:15], v73 offset0:36 offset1:37
	ds_read2st64_b32 v[20:21], v73 offset0:52 offset1:53
	s_waitcnt lgkmcnt(1)
	v_pk_add_f32 v[8:9], v[8:9], v[14:15]
	s_waitcnt lgkmcnt(0)
	v_pk_add_f32 v[8:9], v[8:9], v[20:21]
	s_nop 0
	v_pk_add_f32 v[8:9], v[16:17], v[8:9]
	ds_read2st64_b32 v[14:15], v73 offset0:22 offset1:23
	ds_read2st64_b32 v[16:17], v73 offset0:38 offset1:39
	ds_read2st64_b32 v[20:21], v73 offset0:54 offset1:55
	s_waitcnt lgkmcnt(1)
	v_pk_add_f32 v[14:15], v[14:15], v[16:17]
	s_waitcnt lgkmcnt(0)
	v_pk_add_f32 v[14:15], v[14:15], v[20:21]
	s_nop 0
	v_pk_add_f32 v[14:15], v[18:19], v[14:15]
	ds_read2st64_b32 v[16:17], v73 offset0:24 offset1:25
	ds_read2st64_b32 v[18:19], v73 offset0:40 offset1:41
	ds_read2st64_b32 v[20:21], v73 offset0:56 offset1:57
	s_waitcnt lgkmcnt(1)
	v_pk_add_f32 v[16:17], v[16:17], v[18:19]
	s_waitcnt lgkmcnt(0)
	v_pk_add_f32 v[16:17], v[16:17], v[20:21]
	s_nop 0
	v_pk_add_f32 v[4:5], v[4:5], v[16:17]
	ds_read2st64_b32 v[16:17], v73 offset0:26 offset1:27
	ds_read2st64_b32 v[18:19], v73 offset0:42 offset1:43
	ds_read2st64_b32 v[20:21], v73 offset0:58 offset1:59
	s_waitcnt lgkmcnt(1)
	v_pk_add_f32 v[16:17], v[16:17], v[18:19]
	s_waitcnt lgkmcnt(0)
	v_pk_add_f32 v[16:17], v[16:17], v[20:21]
	s_nop 0
	v_pk_add_f32 v[6:7], v[6:7], v[16:17]
	ds_read2st64_b32 v[16:17], v73 offset0:28 offset1:29
	ds_read2st64_b32 v[18:19], v73 offset0:44 offset1:45
	ds_read2st64_b32 v[20:21], v73 offset0:60 offset1:61
	s_waitcnt lgkmcnt(1)
	v_pk_add_f32 v[16:17], v[16:17], v[18:19]
	s_waitcnt lgkmcnt(0)
	v_pk_add_f32 v[16:17], v[16:17], v[20:21]
	s_nop 0
	v_pk_add_f32 v[0:1], v[0:1], v[16:17]
	ds_read2st64_b32 v[16:17], v73 offset0:30 offset1:31
	ds_read2st64_b32 v[18:19], v73 offset0:46 offset1:47
	ds_read2st64_b32 v[20:21], v73 offset0:62 offset1:63
	s_waitcnt lgkmcnt(1)
	v_pk_add_f32 v[16:17], v[16:17], v[18:19]
	s_waitcnt lgkmcnt(0)
	v_pk_add_f32 v[16:17], v[16:17], v[20:21]
	s_nop 0
	v_pk_add_f32 v[2:3], v[2:3], v[16:17]
	s_cbranch_scc0 .LBB0_361
	v_cndmask_b32_e64 v18, 1.0, 0, s[6:7]
	s_lshl_b32 s6, s20, 5
	s_lshl_b32 s7, s14, 4
	s_or_b32 s6, s6, s7
	s_lshr_b32 s7, s21, 6
	s_or_b32 s6, s6, s7
	v_readlane_b32 s52, v251, 0
	s_lshl_b32 s6, s6, 13
	v_readlane_b32 s62, v251, 10
	v_readlane_b32 s63, v251, 11
	s_add_u32 s6, s62, s6
	s_addc_u32 s7, s63, 0
	s_lshr_b32 s10, s19, 2
	s_and_b32 s10, s10, 4
	v_and_b32_e32 v16, 35, v75
	v_or3_b32 v16, s10, v74, v16
	v_lshlrev_b32_e32 v188, 1, v16
	v_mul_f32_e32 v19, v18, v12
	v_lshl_add_u64 v[16:17], s[6:7], 0, v[188:189]
	v_bfe_u32 v20, v19, 16, 1
	s_movk_i32 s6, 0x7fff
	v_mov_b32_e32 v65, v189
	v_add3_u32 v19, v19, v20, s6
	v_lshl_add_u64 v[16:17], v[16:17], 0, v[64:65]
	global_store_short_d16_hi v[16:17], v19, off
	v_mul_f32_e32 v19, v18, v13
	v_bfe_u32 v20, v19, 16, 1
	v_add3_u32 v19, v19, v20, s6
	global_store_short_d16_hi v[16:17], v19, off offset:128
	v_mul_f32_e32 v19, v18, v10
	v_bfe_u32 v20, v19, 16, 1
	v_add3_u32 v19, v19, v20, s6
	global_store_short_d16_hi v[16:17], v19, off offset:256
	v_mul_f32_e32 v19, v18, v11
	v_bfe_u32 v20, v19, 16, 1
	v_add3_u32 v19, v19, v20, s6
	global_store_short_d16_hi v[16:17], v19, off offset:384
	v_mul_f32_e32 v19, v18, v8
	v_bfe_u32 v20, v19, 16, 1
	v_add3_u32 v19, v19, v20, s6
	global_store_short_d16_hi v[16:17], v19, off offset:2048
	v_mul_f32_e32 v19, v18, v9
	v_bfe_u32 v20, v19, 16, 1
	v_add3_u32 v19, v19, v20, s6
	global_store_short_d16_hi v[16:17], v19, off offset:2176
	v_mul_f32_e32 v19, v18, v14
	v_bfe_u32 v20, v19, 16, 1
	v_add3_u32 v19, v19, v20, s6
	global_store_short_d16_hi v[16:17], v19, off offset:2304
	v_mul_f32_e32 v19, v18, v15
	v_bfe_u32 v20, v19, 16, 1
	v_add3_u32 v19, v19, v20, s6
	global_store_short_d16_hi v[16:17], v19, off offset:2432
	v_mul_f32_e32 v19, v18, v4
	v_bfe_u32 v20, v19, 16, 1
	v_add_co_u32_e32 v16, vcc, s35, v16
	v_add3_u32 v19, v19, v20, s6
	s_nop 0
	v_addc_co_u32_e32 v17, vcc, 0, v17, vcc
	global_store_short_d16_hi v[16:17], v19, off
	v_mul_f32_e32 v19, v18, v5
	v_bfe_u32 v20, v19, 16, 1
	v_add3_u32 v19, v19, v20, s6
	global_store_short_d16_hi v[16:17], v19, off offset:128
	v_mul_f32_e32 v19, v18, v6
	v_bfe_u32 v20, v19, 16, 1
	v_add3_u32 v19, v19, v20, s6
	global_store_short_d16_hi v[16:17], v19, off offset:256
	v_mul_f32_e32 v19, v18, v7
	v_bfe_u32 v20, v19, 16, 1
	v_add3_u32 v19, v19, v20, s6
	global_store_short_d16_hi v[16:17], v19, off offset:384
	v_mul_f32_e32 v19, v18, v0
	v_bfe_u32 v20, v19, 16, 1
	v_add3_u32 v19, v19, v20, s6
	global_store_short_d16_hi v[16:17], v19, off offset:2048
	v_mul_f32_e32 v19, v18, v1
	v_bfe_u32 v20, v19, 16, 1
	v_add3_u32 v19, v19, v20, s6
	global_store_short_d16_hi v[16:17], v19, off offset:2176
	v_mul_f32_e32 v19, v18, v2
	v_bfe_u32 v20, v19, 16, 1
	v_add3_u32 v19, v19, v20, s6
	v_mul_f32_e32 v18, v18, v3
	global_store_short_d16_hi v[16:17], v19, off offset:2304
	v_bfe_u32 v19, v18, 16, 1
	v_add3_u32 v18, v18, v19, s6
	v_readlane_b32 s53, v251, 1
	v_readlane_b32 s54, v251, 2
	v_readlane_b32 s55, v251, 3
	v_readlane_b32 s56, v251, 4
	v_readlane_b32 s57, v251, 5
	v_readlane_b32 s58, v251, 6
	v_readlane_b32 s59, v251, 7
	v_readlane_b32 s60, v251, 8
	v_readlane_b32 s61, v251, 9
	v_readlane_b32 s64, v251, 12
	v_readlane_b32 s65, v251, 13
	v_readlane_b32 s66, v251, 14
	v_readlane_b32 s67, v251, 15
	global_store_short_d16_hi v[16:17], v18, off offset:2432
	s_mov_b64 s[10:11], 0

; template <int EPI> ...
;     ...
;     const int idx0 = blockIdx.x >> 3;
;     if (idx0 < perX) {
;         int mt0, nt0; tile_of(idx0, mt0, nt0);
;         const bf16_t* A0 = A + (size_t)(mt0 * 128 + lrow) * K + lcc * 8;
;         const bf16_t* B0 = Bt + (size_t)(nt0 * 256 + lrowp) * K + lcc * 8;
;         G_LOAD(A0, B0, 0);
;         G_STORE(0);
;         G_LOAD(A0, B0, 1);
;         __syncthreads();
;     }
;     for (int idx = idx0; idx < perX; idx += nbx) {
;         int mt, nt; tile_of(idx, mt, nt);
;         int mtn, ntn; tile_of(idx + nbx < perX ? idx + nbx : idx, mtn, ntn);
;         const bf16_t* Ag = A + (size_t)(mt * 128 + lrow) * K + lcc * 8;
;         const bf16_t* Bg = Bt + (size_t)(nt * 256 + lrowp) * K + lcc * 8;
;         const bf16_t* An = A + (size_t)(mtn * 128 + lrow) * K + lcc * 8;
;         const bf16_t* Bn = Bt + (size_t)(ntn * 256 + lrowp) * K + lcc * 8;
;         f32x4 acc[4][8];
; #pragma unroll
;         for (int i = 0; i < 4; ++i)
; #pragma unroll
;             for (int j = 0; j < 8; ++j) {
;                 if (EPI == 2)
;                     acc[i][j] = *(const f32x4*)(xin + (size_t)(mt * 128 + wr * 64 + i * 16 + fr) * Nn + nt * 256 + wc * 128 + 32 * (j >> 1) + 8 * fq + 4 * (j & 1));
;                 else acc[i][j] = (f32x4){0.f, 0.f, 0.f, 0.f};
;             }
;         for (int kt = 0; kt < nk; ++kt) {
;             const int buf = kt & 1;
;             const bf16_t* a_ = sA + buf * 128 * 40 + (wr * 64 + fr) * 40 + fq * 8;
;             const bf16_t* b_ = sB + buf * 256 * 40 + (wc * 128 + fr) * 40 + fq * 8;
;             bf16x8 af[4];
; #pragma unroll
;             for (int i = 0; i < 4; ++i) af[i] = *(const bf16x8*)(a_ + i * 16 * 40);
; #pragma unroll
;             for (int jh = 0; jh < 2; ++jh) {
;                 bf16x8 bfr[4];
; #pragma unroll
;                 for (int j = 0; j < 4; ++j) bfr[j] = *(const bf16x8*)(b_ + (jh * 4 + j) * 16 * 40);
; #pragma unroll
;                 for (int i = 0; i < 4; ++i)
; #pragma unroll
;                     for (int j = 0; j < 4; ++j) acc[i][jh * 4 + j] = mfma(bfr[j], af[i], acc[i][jh * 4 + j]);
;             }
;             G_STORE(buf ^ 1);
;             {
;                 const bool cur = kt + 2 < nk;
;                 const bf16_t* pa = cur ? Ag : An; const bf16_t* pb = cur ? Bg : Bn;
;                 const int st = cur ? kt + 2 : kt + 2 - nk;
;                 G_LOAD(pa, pb, st);
.LBB0_691:
	v_readlane_b32 s21, v253, 4
	v_readlane_b32 s22, v253, 6
	v_readlane_b32 s23, v253, 5
	s_nop 3
	s_cmp_eq_u32 s23, 0
	s_cbranch_scc1 .Lg691_entry
	v_and_b32_e32 v8, 63, v210
	v_lshrrev_b32_e32 v9, 6, v210
	s_nop 0
	v_readfirstlane_b32 s23, v9
	v_lshrrev_b32_e32 v9, 4, v8
	v_sub_u32_e32 v10, 0, v9
	v_and_b32_e32 v10, 3, v10
	v_and_b32_e32 v11, 3, v8
	v_xor_b32_e32 v11, v11, v10
	v_lshrrev_b32_e32 v12, 2, v8
	v_lshlrev_b32_e32 v0, 11, v12
	v_lshl_add_u32 v0, v11, 4, v0
	s_lshl_b32 vcc_lo, s23, 16
	v_add_u32_e32 v0, vcc_lo, v0
	v_add_u32_e32 v0, 0x1000, v0
	v_add_u32_e32 v1, 0x7c00, v0
	v_and_b32_e32 v13, 3, v12
	v_lshl_add_u32 v13, v9, 3, v13
	v_lshlrev_b32_e32 v2, 11, v13
	v_lshl_add_u32 v2, v11, 4, v2
	s_lshl_b32 vcc_lo, s23, 17
	v_add_u32_e32 v2, vcc_lo, v2
	v_add_u32_e32 v2, 0x800, v2
	v_add_u32_e32 v3, 0x1c00, v2
	v_add_u32_e32 v4, 0x10800, v2
	v_add_u32_e32 v5, 0x12400, v2
	v_and_b32_e32 v10, 15, v8
	v_lshrrev_b32_e32 v11, 2, v10
	v_sub_u32_e32 v11, 0, v11
	v_and_b32_e32 v11, 3, v11
	v_xor_b32_e32 v11, v9, v11
	v_lshlrev_b32_e32 v6, 6, v10
	v_lshl_add_u32 v6, v11, 4, v6
	s_lshr_b32 vcc_lo, s23, 1
	s_mul_i32 vcc_lo, vcc_lo, 0x3000
	s_and_b32 vcc_hi, s23, 1
	s_mul_i32 vcc_hi, vcc_hi, 0x3000
	s_add_u32 vcc_hi, vcc_hi, 0x800
	v_add_u32_e32 v7, vcc_hi, v6
	v_add_u32_e32 v6, vcc_lo, v6
	s_mul_i32 s22, s23, 0x1800
	v_writelane_b32 v253, s22, 6
	v_writelane_b32 v253, 0, 5
	v_readlane_b32 vcc_lo, v253, 0
	v_readlane_b32 vcc_hi, v253, 1
	s_lshl_b32 s23, s8, 18
	s_nop 1
	s_add_u32 s98, vcc_lo, s23
	s_addc_u32 s99, vcc_hi, 0
	s_sub_u32 s98, s98, 0x1000
	s_subb_u32 s99, s99, 0
	v_readlane_b32 vcc_lo, v253, 2
	v_readlane_b32 vcc_hi, v253, 3
	s_lshl_b32 s23, s9, 19
	s_nop 1
	s_add_u32 s100, vcc_lo, s23
	s_addc_u32 s101, vcc_hi, 0
	s_sub_u32 s100, s100, 0x1000
	s_subb_u32 s101, s101, 0
	s_add_u32 m0, s21, s22
	s_nop 0
	global_load_lds_dwordx4 v0, s[98:99]
	global_load_lds_dwordx4 v1, s[98:99] offset:1024
	global_load_lds_dwordx4 v2, s[100:101] offset:2048
	global_load_lds_dwordx4 v3, s[100:101] offset:3072
	s_add_u32 m0, m0, 0x1000
	s_nop 0
	global_load_lds_dwordx4 v4, s[100:101]
	global_load_lds_dwordx4 v5, s[100:101] offset:1024
	s_add_u32 s98, s98, 64
	s_addc_u32 s99, s99, 0
	s_add_u32 s100, s100, 64
	s_addc_u32 s101, s101, 0
	s_add_u32 s23, s21, 0x6000
	s_cmp_eq_u32 s23, 0x12000
	s_cselect_b32 s23, 0, s23
	s_add_u32 m0, s23, s22
	s_nop 0
	global_load_lds_dwordx4 v0, s[98:99]
	global_load_lds_dwordx4 v1, s[98:99] offset:1024
	global_load_lds_dwordx4 v2, s[100:101] offset:2048
	global_load_lds_dwordx4 v3, s[100:101] offset:3072
	s_add_u32 m0, m0, 0x1000
	s_nop 0
	global_load_lds_dwordx4 v4, s[100:101]
	global_load_lds_dwordx4 v5, s[100:101] offset:1024
	s_add_u32 s98, s98, 64
	s_addc_u32 s99, s99, 0
	s_add_u32 s100, s100, 64
	s_addc_u32 s101, s101, 0
	s_add_u32 s23, s23, 0x6000
	s_cmp_eq_u32 s23, 0x12000
	s_cselect_b32 s23, 0, s23
	s_add_u32 m0, s23, s22
	s_nop 0
	global_load_lds_dwordx4 v0, s[98:99]
	global_load_lds_dwordx4 v1, s[98:99] offset:1024
	global_load_lds_dwordx4 v2, s[100:101] offset:2048
	global_load_lds_dwordx4 v3, s[100:101] offset:3072
	s_add_u32 m0, m0, 0x1000
	s_nop 0
	global_load_lds_dwordx4 v4, s[100:101]
	global_load_lds_dwordx4 v5, s[100:101] offset:1024
	s_add_u32 s98, s98, 64
	s_addc_u32 s99, s99, 0
	s_add_u32 s100, s100, 64
	s_addc_u32 s101, s101, 0
.Lg691_entry:
	s_mov_b32 s20, 0
	s_waitcnt vmcnt(0)
	s_barrier
	v_add_u32_e32 v8, s21, v6
	v_add_u32_e32 v9, s21, v7
	ds_read_b128 v[174:177], v9
	ds_read_b128 v[192:195], v9 offset:1024
	ds_read_b128 v[196:199], v9 offset:2048
	ds_read_b128 v[200:203], v9 offset:3072
	ds_read_b128 v[10:13], v8
	ds_read_b128 v[14:17], v8 offset:1024
	ds_read_b128 v[18:21], v8 offset:6144
	ds_read_b128 v[154:157], v8 offset:7168
	ds_read_b128 v[204:207], v9 offset:6144
	ds_read_b128 v[232:235], v9 offset:7168
	ds_read_b128 v[236:239], v9 offset:8192
	ds_read_b128 v[240:243], v9 offset:9216
.Lg691_top:
	s_waitcnt lgkmcnt(4)
	v_mfma_f32_16x16x32_bf16 v[148:151], v[174:177], v[10:13], v[148:151]
	v_mfma_f32_16x16x32_bf16 v[116:119], v[174:177], v[14:17], v[116:119]
	v_mfma_f32_16x16x32_bf16 v[84:87], v[174:177], v[18:21], v[84:87]
	v_mfma_f32_16x16x32_bf16 v[52:55], v[174:177], v[154:157], v[52:55]
	v_mfma_f32_16x16x32_bf16 v[144:147], v[192:195], v[10:13], v[144:147]
	v_mfma_f32_16x16x32_bf16 v[112:115], v[192:195], v[14:17], v[112:115]
	v_mfma_f32_16x16x32_bf16 v[80:83], v[192:195], v[18:21], v[80:83]
	v_mfma_f32_16x16x32_bf16 v[48:51], v[192:195], v[154:157], v[48:51]
	v_mfma_f32_16x16x32_bf16 v[140:143], v[196:199], v[10:13], v[140:143]
	v_mfma_f32_16x16x32_bf16 v[108:111], v[196:199], v[14:17], v[108:111]
	v_mfma_f32_16x16x32_bf16 v[76:79], v[196:199], v[18:21], v[76:79]
	v_mfma_f32_16x16x32_bf16 v[44:47], v[196:199], v[154:157], v[44:47]
	v_mfma_f32_16x16x32_bf16 v[136:139], v[200:203], v[10:13], v[136:139]
	v_mfma_f32_16x16x32_bf16 v[104:107], v[200:203], v[14:17], v[104:107]
	v_mfma_f32_16x16x32_bf16 v[72:75], v[200:203], v[18:21], v[72:75]
	v_mfma_f32_16x16x32_bf16 v[40:43], v[200:203], v[154:157], v[40:43]
	s_waitcnt vmcnt(6)
	s_waitcnt lgkmcnt(0)
	s_barrier
	s_add_u32 s23, s21, 0x6000
	s_cmp_eq_u32 s23, 0x12000
	s_cselect_b32 s23, 0, s23
	v_add_u32_e32 v8, s23, v6
	v_add_u32_e32 v9, s23, v7
	ds_read_b128 v[174:177], v9
	ds_read_b128 v[192:195], v9 offset:1024
	ds_read_b128 v[196:199], v9 offset:2048
	ds_read_b128 v[200:203], v9 offset:3072
	s_cmp_eq_u32 s20, 29
	s_cbranch_scc1 .Lg691_sw
; DI f32x4 mfma(bf16x8 a, bf16x8 b, f32x4 c) { return __builtin_amdgcn_mfma_f32_16x16x32_bf16(a, b, c, 0, 0, 0); }
; #define G_LOAD(PA, PB, STEP) do { _Pragma("unroll") for (int i_ = 0; i_ < 2; ++i_) ra[i_] = *(const u32x4*)((PA) + (size_t)(64 * i_) * K + (STEP) * 32); \
;         _Pragma("unroll") for (int i_ = 0; i_ < 4; ++i_) rb[i_] = *(const u32x4*)((PB) + (size_t)(64 * i_) * K + (STEP) * 32); } while (0)
; #define G_STORE(BUF) do { _Pragma("unroll") for (int i_ = 0; i_ < 2; ++i_) *(u32x4*)(sA + (BUF) * 128 * 40 + (lrow + 64 * i_) * 40 + lcc * 8) = ra[i_]; \
;         _Pragma("unroll") for (int i_ = 0; i_ < 4; ++i_) *(u32x4*)(sB + (BUF) * 256 * 40 + (lrow + 64 * i_) * 40 + lcc * 8) = rb[i_]; } while (0)
; template <int EPI> ...
;     ...
;         for (int kt = 0; kt < nk; ++kt) {
;             const int buf = kt & 1;
;             const bf16_t* a_ = sA + buf * 128 * 40 + (wr * 64 + fr) * 40 + fq * 8;
;             const bf16_t* b_ = sB + buf * 256 * 40 + (wc * 128 + fr) * 40 + fq * 8;
;             bf16x8 af[4];
; #pragma unroll
;             for (int i = 0; i < 4; ++i) af[i] = *(const bf16x8*)(a_ + i * 16 * 40);
; #pragma unroll
;             for (int jh = 0; jh < 2; ++jh) {
;                 bf16x8 bfr[4];
; #pragma unroll
;                 for (int j = 0; j < 4; ++j) bfr[j] = *(const bf16x8*)(b_ + (jh * 4 + j) * 16 * 40);
; #pragma unroll
;                 for (int i = 0; i < 4; ++i)
; #pragma unroll
;                     for (int j = 0; j < 4; ++j) acc[i][jh * 4 + j] = mfma(bfr[j], af[i], acc[i][jh * 4 + j]);
;             }
;             G_STORE(buf ^ 1);
;             {
;                 const bool cur = kt + 2 < nk;
;                 const bf16_t* pa = cur ? Ag : An; const bf16_t* pb = cur ? Bg : Bn;
;                 const int st = cur ? kt + 2 : kt + 2 - nk;
;                 G_LOAD(pa, pb, st);
;             }
;             __syncthreads();
;         }
.Lg691_swret:
	s_add_u32 m0, s21, s22
	v_mfma_f32_16x16x32_bf16 v[132:135], v[204:207], v[10:13], v[132:135]
	global_load_lds_dwordx4 v0, s[98:99]
	v_mfma_f32_16x16x32_bf16 v[128:131], v[232:235], v[10:13], v[128:131]
	v_mfma_f32_16x16x32_bf16 v[124:127], v[236:239], v[10:13], v[124:127]
	global_load_lds_dwordx4 v1, s[98:99] offset:1024
	v_mfma_f32_16x16x32_bf16 v[120:123], v[240:243], v[10:13], v[120:123]
	ds_read_b128 v[10:13], v8
	v_mfma_f32_16x16x32_bf16 v[100:103], v[204:207], v[14:17], v[100:103]
	global_load_lds_dwordx4 v2, s[100:101] offset:2048
	v_mfma_f32_16x16x32_bf16 v[96:99], v[232:235], v[14:17], v[96:99]
	v_mfma_f32_16x16x32_bf16 v[92:95], v[236:239], v[14:17], v[92:95]
	global_load_lds_dwordx4 v3, s[100:101] offset:3072
	v_mfma_f32_16x16x32_bf16 v[88:91], v[240:243], v[14:17], v[88:91]
	ds_read_b128 v[14:17], v8 offset:1024
	v_mfma_f32_16x16x32_bf16 v[68:71], v[204:207], v[18:21], v[68:71]
	s_add_u32 m0, m0, 0x1000
	v_mfma_f32_16x16x32_bf16 v[64:67], v[232:235], v[18:21], v[64:67]
	global_load_lds_dwordx4 v4, s[100:101]
	v_mfma_f32_16x16x32_bf16 v[60:63], v[236:239], v[18:21], v[60:63]
	v_mfma_f32_16x16x32_bf16 v[56:59], v[240:243], v[18:21], v[56:59]
	ds_read_b128 v[18:21], v8 offset:6144
	v_mfma_f32_16x16x32_bf16 v[36:39], v[204:207], v[154:157], v[36:39]
	global_load_lds_dwordx4 v5, s[100:101] offset:1024
	v_mfma_f32_16x16x32_bf16 v[32:35], v[232:235], v[154:157], v[32:35]
	v_mfma_f32_16x16x32_bf16 v[28:31], v[236:239], v[154:157], v[28:31]
	v_mfma_f32_16x16x32_bf16 v[24:27], v[240:243], v[154:157], v[24:27]
	ds_read_b128 v[154:157], v8 offset:7168
	ds_read_b128 v[204:207], v9 offset:6144
	ds_read_b128 v[232:235], v9 offset:7168
	ds_read_b128 v[236:239], v9 offset:8192
	ds_read_b128 v[240:243], v9 offset:9216
	s_add_u32 s98, s98, 64
	s_addc_u32 s99, s99, 0
	s_add_u32 s100, s100, 64
	s_addc_u32 s101, s101, 0
	s_add_u32 s21, s21, 0x6000
	s_cmp_eq_u32 s21, 0x12000
	s_cselect_b32 s21, 0, s21
	s_add_u32 s20, s20, 1
	s_cmp_lt_u32 s20, 31
	s_cbranch_scc1 .Lg691_top
	s_waitcnt lgkmcnt(4)
	v_mfma_f32_16x16x32_bf16 v[148:151], v[174:177], v[10:13], v[148:151]
	v_mfma_f32_16x16x32_bf16 v[116:119], v[174:177], v[14:17], v[116:119]
	v_mfma_f32_16x16x32_bf16 v[84:87], v[174:177], v[18:21], v[84:87]
	v_mfma_f32_16x16x32_bf16 v[52:55], v[174:177], v[154:157], v[52:55]
	v_mfma_f32_16x16x32_bf16 v[144:147], v[192:195], v[10:13], v[144:147]
	v_mfma_f32_16x16x32_bf16 v[112:115], v[192:195], v[14:17], v[112:115]
	v_mfma_f32_16x16x32_bf16 v[80:83], v[192:195], v[18:21], v[80:83]
	v_mfma_f32_16x16x32_bf16 v[48:51], v[192:195], v[154:157], v[48:51]
	v_mfma_f32_16x16x32_bf16 v[140:143], v[196:199], v[10:13], v[140:143]
	v_mfma_f32_16x16x32_bf16 v[108:111], v[196:199], v[14:17], v[108:111]
	v_mfma_f32_16x16x32_bf16 v[76:79], v[196:199], v[18:21], v[76:79]
	v_mfma_f32_16x16x32_bf16 v[44:47], v[196:199], v[154:157], v[44:47]
	v_mfma_f32_16x16x32_bf16 v[136:139], v[200:203], v[10:13], v[136:139]
	v_mfma_f32_16x16x32_bf16 v[104:107], v[200:203], v[14:17], v[104:107]
	v_mfma_f32_16x16x32_bf16 v[72:75], v[200:203], v[18:21], v[72:75]
	v_mfma_f32_16x16x32_bf16 v[40:43], v[200:203], v[154:157], v[40:43]
	s_waitcnt vmcnt(6)
	s_waitcnt lgkmcnt(0)
	s_barrier
	s_add_u32 m0, s21, s22
	v_mfma_f32_16x16x32_bf16 v[132:135], v[204:207], v[10:13], v[132:135]
	global_load_lds_dwordx4 v0, s[98:99]
	v_mfma_f32_16x16x32_bf16 v[128:131], v[232:235], v[10:13], v[128:131]
	v_mfma_f32_16x16x32_bf16 v[124:127], v[236:239], v[10:13], v[124:127]
	global_load_lds_dwordx4 v1, s[98:99] offset:1024
	v_mfma_f32_16x16x32_bf16 v[120:123], v[240:243], v[10:13], v[120:123]
	v_mfma_f32_16x16x32_bf16 v[100:103], v[204:207], v[14:17], v[100:103]
	global_load_lds_dwordx4 v2, s[100:101] offset:2048
	v_mfma_f32_16x16x32_bf16 v[96:99], v[232:235], v[14:17], v[96:99]
	v_mfma_f32_16x16x32_bf16 v[92:95], v[236:239], v[14:17], v[92:95]
	global_load_lds_dwordx4 v3, s[100:101] offset:3072
	v_mfma_f32_16x16x32_bf16 v[88:91], v[240:243], v[14:17], v[88:91]
	v_mfma_f32_16x16x32_bf16 v[68:71], v[204:207], v[18:21], v[68:71]
	s_add_u32 m0, m0, 0x1000
	v_mfma_f32_16x16x32_bf16 v[64:67], v[232:235], v[18:21], v[64:67]
	global_load_lds_dwordx4 v4, s[100:101]
	v_mfma_f32_16x16x32_bf16 v[60:63], v[236:239], v[18:21], v[60:63]
	v_mfma_f32_16x16x32_bf16 v[56:59], v[240:243], v[18:21], v[56:59]
	v_mfma_f32_16x16x32_bf16 v[36:39], v[204:207], v[154:157], v[36:39]
	global_load_lds_dwordx4 v5, s[100:101] offset:1024
	v_mfma_f32_16x16x32_bf16 v[32:35], v[232:235], v[154:157], v[32:35]
	v_mfma_f32_16x16x32_bf16 v[28:31], v[236:239], v[154:157], v[28:31]
	v_mfma_f32_16x16x32_bf16 v[24:27], v[240:243], v[154:157], v[24:27]
	s_add_u32 s98, s98, 64
	s_addc_u32 s99, s99, 0
	s_add_u32 s100, s100, 64
	s_addc_u32 s101, s101, 0
	s_add_u32 s21, s21, 0x6000
	s_cmp_eq_u32 s21, 0x12000
	s_cselect_b32 s21, 0, s21
	s_add_u32 s20, s20, 1
	s_branch .Lg691_end
; DI unsigned pk2(float lo, float hi) { f32x2 v = {lo, hi}; bf16x2_t r = __builtin_convertvector(v, bf16x2_t); return __builtin_bit_cast(unsigned, r); }
; template <int EPI> ...
;     ...
;         int mtn, ntn; tile_of(idx + nbx < perX ? idx + nbx : idx, mtn, ntn);
;         const bf16_t* Ag = A + (size_t)(mt * 128 + lrow) * K + lcc * 8;
;         const bf16_t* Bg = Bt + (size_t)(nt * 256 + lrowp) * K + lcc * 8;
;         const bf16_t* An = A + (size_t)(mtn * 128 + lrow) * K + lcc * 8;
;         const bf16_t* Bn = Bt + (size_t)(ntn * 256 + lrowp) * K + lcc * 8;
;     ...
;                 } else {
;                     *(f32x4*)(xout + (size_t)m * Nn + n0) = v0;
;                     *(f32x4*)(xout + (size_t)m * Nn + n0 + 4) = v1;
;                     if (hb) {
;                         const f32x4 g0 = *(const f32x4*)(gn + n0), g1 = *(const f32x4*)(gn + n0 + 4);
;                         u32x4 o4; o4[0] = pk2(v0[0] * g0[0], v0[1] * g0[1]); o4[1] = pk2(v0[2] * g0[2], v0[3] * g0[3]);
;                         o4[2] = pk2(v1[0] * g1[0], v1[1] * g1[1]); o4[3] = pk2(v1[2] * g1[2], v1[3] * g1[3]);
;                         *(u32x4*)(hb + (size_t)m * Nn + n0) = o4;
;                         sq += v0[0] * v0[0] + v0[1] * v0[1] + v0[2] * v0[2] + v0[3] * v0[3] + v1[0] * v1[0] + v1[1] * v1[1] + v1[2] * v1[2] + v1[3] * v1[3];
;                     }
.Lg691_sw:
	v_readlane_b32 vcc_lo, v253, 0
	v_readlane_b32 vcc_hi, v253, 1
	s_lshl_b32 s23, s17, 18
	s_nop 1
	s_add_u32 s98, vcc_lo, s23
	s_addc_u32 s99, vcc_hi, 0
	s_sub_u32 s98, s98, 0x1000
	s_subb_u32 s99, s99, 0
	v_readlane_b32 vcc_lo, v253, 2
	v_readlane_b32 vcc_hi, v253, 3
	s_lshl_b32 s23, s19, 19
	s_nop 1
	s_add_u32 s100, vcc_lo, s23
	s_addc_u32 s101, vcc_hi, 0
	s_sub_u32 s100, s100, 0x1000
	s_subb_u32 s101, s101, 0
	s_branch .Lg691_swret
.Lg691_end:
	v_writelane_b32 v253, s21, 4
	v_readlane_b32 s52, v251, 34
	v_readlane_b32 s53, v251, 35
	v_readlane_b32 s54, v251, 36
	v_readlane_b32 s55, v251, 37
	v_readlane_b32 s56, v251, 38
	v_readlane_b32 s57, v251, 39
	v_readlane_b32 s58, v251, 40
	v_readlane_b32 s59, v251, 41
	v_readlane_b32 s60, v251, 42
	v_readlane_b32 s61, v251, 43
	v_readlane_b32 s62, v251, 44
	v_readlane_b32 s63, v251, 45
	v_readlane_b32 s64, v251, 46
	v_readlane_b32 s65, v251, 47
	v_readlane_b32 s66, v251, 48
	v_readlane_b32 s67, v251, 49
	v_or_b32_e32 v185, s16, v183
	v_lshl_add_u64 v[164:165], s[56:57], 0, v[164:165]
	v_readlane_b32 s52, v251, 0
	v_lshlrev_b64 v[174:175], 11, v[158:159]
	v_readlane_b32 s66, v251, 14
	v_readlane_b32 s67, v251, 15
	v_lshlrev_b32_e32 v188, 2, v185
	v_lshl_add_u64 v[176:177], v[164:165], 0, v[188:189]
	v_lshl_add_u64 v[174:175], s[66:67], 0, v[174:175]
	s_and_b64 vcc, exec, s[24:25]
	v_lshlrev_b32_e32 v164, 1, v185
	v_readlane_b32 s53, v251, 1
	v_readlane_b32 s54, v251, 2
	v_readlane_b32 s55, v251, 3
	v_readlane_b32 s56, v251, 4
	v_readlane_b32 s57, v251, 5
	v_readlane_b32 s58, v251, 6
	v_readlane_b32 s59, v251, 7
	v_readlane_b32 s60, v251, 8
	v_readlane_b32 s61, v251, 9
	v_readlane_b32 s62, v251, 10
	v_readlane_b32 s63, v251, 11
	v_readlane_b32 s64, v251, 12
	v_readlane_b32 s65, v251, 13
	global_store_dwordx4 v[176:177], v[148:151], off
	global_store_dwordx4 v[176:177], v[144:147], off offset:16
	s_cbranch_vccz .LBB0_694
	global_load_dwordx4 v[192:195], v188, s[12:13] offset:16
	global_load_dwordx4 v[196:199], v188, s[12:13]
	v_mov_b32_e32 v165, v189
	s_waitcnt vmcnt(1)
	v_pk_mul_f32 v[192:193], v[144:145], v[192:193]
	s_waitcnt vmcnt(0)
	v_pk_mul_f32 v[196:197], v[148:149], v[196:197]
	v_pk_mul_f32 v[148:149], v[148:149], v[148:149]
	v_pk_mul_f32 v[186:187], v[150:151], v[198:199]
	v_pk_mul_f32 v[150:151], v[150:151], v[150:151]
	v_add_f32_e32 v148, v148, v149
	v_add_f32_e32 v148, v150, v148
	v_pk_mul_f32 v[144:145], v[144:145], v[144:145]
	v_add_f32_e32 v148, v151, v148
	v_add_f32_e32 v144, v144, v148
	v_cvt_pk_bf16_f32 v196, v196, v197
	v_cvt_pk_bf16_f32 v197, v186, v187
	v_pk_mul_f32 v[186:187], v[146:147], v[194:195]
	v_pk_mul_f32 v[146:147], v[146:147], v[146:147]
	v_add_f32_e32 v144, v145, v144
	v_add_f32_e32 v144, v146, v144
	v_cvt_pk_bf16_f32 v198, v192, v193
	v_cvt_pk_bf16_f32 v199, v186, v187
	v_lshl_add_u64 v[186:187], v[174:175], 0, v[164:165]
	v_add_f32_e32 v144, v147, v144
	global_store_dwordx4 v[186:187], v[196:199], off
	s_branch .LBB0_695

; template <int EPI> ...
;     ...
;     const int idx0 = blockIdx.x >> 3;
;     if (idx0 < perX) {
;         int mt0, nt0; tile_of(idx0, mt0, nt0);
;         const bf16_t* A0 = A + (size_t)(mt0 * 128 + lrow) * K + lcc * 8;
;         const bf16_t* B0 = Bt + (size_t)(nt0 * 256 + lrowp) * K + lcc * 8;
;         G_LOAD(A0, B0, 0);
;         G_STORE(0);
;         G_LOAD(A0, B0, 1);
;         __syncthreads();
;     }
;     for (int idx = idx0; idx < perX; idx += nbx) {
;         int mt, nt; tile_of(idx, mt, nt);
;         int mtn, ntn; tile_of(idx + nbx < perX ? idx + nbx : idx, mtn, ntn);
;         const bf16_t* Ag = A + (size_t)(mt * 128 + lrow) * K + lcc * 8;
;         const bf16_t* Bg = Bt + (size_t)(nt * 256 + lrowp) * K + lcc * 8;
;         const bf16_t* An = A + (size_t)(mtn * 128 + lrow) * K + lcc * 8;
;         const bf16_t* Bn = Bt + (size_t)(ntn * 256 + lrowp) * K + lcc * 8;
;         f32x4 acc[4][8];
; #pragma unroll
;         for (int i = 0; i < 4; ++i)
; #pragma unroll
;             for (int j = 0; j < 8; ++j) {
;                 if (EPI == 2)
;                     acc[i][j] = *(const f32x4*)(xin + (size_t)(mt * 128 + wr * 64 + i * 16 + fr) * Nn + nt * 256 + wc * 128 + 32 * (j >> 1) + 8 * fq + 4 * (j & 1));
;                 else acc[i][j] = (f32x4){0.f, 0.f, 0.f, 0.f};
;             }
;         for (int kt = 0; kt < nk; ++kt) {
;             const int buf = kt & 1;
;             const bf16_t* a_ = sA + buf * 128 * 40 + (wr * 64 + fr) * 40 + fq * 8;
;             const bf16_t* b_ = sB + buf * 256 * 40 + (wc * 128 + fr) * 40 + fq * 8;
;             bf16x8 af[4];
; #pragma unroll
;             for (int i = 0; i < 4; ++i) af[i] = *(const bf16x8*)(a_ + i * 16 * 40);
; #pragma unroll
;             for (int jh = 0; jh < 2; ++jh) {
;                 bf16x8 bfr[4];
; #pragma unroll
;                 for (int j = 0; j < 4; ++j) bfr[j] = *(const bf16x8*)(b_ + (jh * 4 + j) * 16 * 40);
; #pragma unroll
;                 for (int i = 0; i < 4; ++i)
; #pragma unroll
;                     for (int j = 0; j < 4; ++j) acc[i][jh * 4 + j] = mfma(bfr[j], af[i], acc[i][jh * 4 + j]);
;             }
;             G_STORE(buf ^ 1);
;             {
;                 const bool cur = kt + 2 < nk;
;                 const bf16_t* pa = cur ? Ag : An; const bf16_t* pb = cur ? Bg : Bn;
;                 const int st = cur ? kt + 2 : kt + 2 - nk;
;                 G_LOAD(pa, pb, st);
.LBB0_778:
	v_readlane_b32 s16, v253, 4
	v_readlane_b32 s17, v253, 6
	v_readlane_b32 s18, v253, 5
	s_nop 3
	s_cmp_eq_u32 s18, 0
	s_cbranch_scc1 .Lg778_entry
	v_and_b32_e32 v8, 63, v210
	v_lshrrev_b32_e32 v9, 6, v210
	s_nop 0
	v_readfirstlane_b32 s18, v9
	v_lshrrev_b32_e32 v9, 4, v8
	v_sub_u32_e32 v10, 0, v9
	v_and_b32_e32 v10, 3, v10
	v_and_b32_e32 v11, 3, v8
	v_xor_b32_e32 v11, v11, v10
	v_lshrrev_b32_e32 v12, 2, v8
	v_lshlrev_b32_e32 v0, 11, v12
	v_lshl_add_u32 v0, v11, 4, v0
	s_lshl_b32 vcc_lo, s18, 16
	v_add_u32_e32 v0, vcc_lo, v0
	v_add_u32_e32 v0, 0x1000, v0
	v_add_u32_e32 v1, 0x7c00, v0
	v_and_b32_e32 v13, 3, v12
	v_lshl_add_u32 v13, v9, 3, v13
	v_lshlrev_b32_e32 v2, 11, v13
	v_lshl_add_u32 v2, v11, 4, v2
	s_lshl_b32 vcc_lo, s18, 17
	v_add_u32_e32 v2, vcc_lo, v2
	v_add_u32_e32 v2, 0x800, v2
	v_add_u32_e32 v3, 0x1c00, v2
	v_add_u32_e32 v4, 0x10800, v2
	v_add_u32_e32 v5, 0x12400, v2
	v_and_b32_e32 v10, 15, v8
	v_lshrrev_b32_e32 v11, 2, v10
	v_sub_u32_e32 v11, 0, v11
	v_and_b32_e32 v11, 3, v11
	v_xor_b32_e32 v11, v9, v11
	v_lshlrev_b32_e32 v6, 6, v10
	v_lshl_add_u32 v6, v11, 4, v6
	s_lshr_b32 vcc_lo, s18, 1
	s_mul_i32 vcc_lo, vcc_lo, 0x3000
	s_and_b32 vcc_hi, s18, 1
	s_mul_i32 vcc_hi, vcc_hi, 0x3000
	s_add_u32 vcc_hi, vcc_hi, 0x800
	v_add_u32_e32 v7, vcc_hi, v6
	v_add_u32_e32 v6, vcc_lo, v6
	s_mul_i32 s17, s18, 0x1800
	v_writelane_b32 v253, s17, 6
	v_writelane_b32 v253, 0, 5
	v_readlane_b32 vcc_lo, v253, 0
	v_readlane_b32 vcc_hi, v253, 1
	s_lshl_b32 s18, s7, 18
	s_nop 1
	s_add_u32 s98, vcc_lo, s18
	s_addc_u32 s99, vcc_hi, 0
	s_sub_u32 s98, s98, 0x1000
	s_subb_u32 s99, s99, 0
	v_readlane_b32 vcc_lo, v253, 2
	v_readlane_b32 vcc_hi, v253, 3
	s_lshl_b32 s18, s6, 19
	s_nop 1
	s_add_u32 s100, vcc_lo, s18
	s_addc_u32 s101, vcc_hi, 0
	s_sub_u32 s100, s100, 0x1000
	s_subb_u32 s101, s101, 0
	s_add_u32 m0, s16, s17
	s_nop 0
	global_load_lds_dwordx4 v0, s[98:99]
	global_load_lds_dwordx4 v1, s[98:99] offset:1024
	global_load_lds_dwordx4 v2, s[100:101] offset:2048
	global_load_lds_dwordx4 v3, s[100:101] offset:3072
	s_add_u32 m0, m0, 0x1000
	s_nop 0
	global_load_lds_dwordx4 v4, s[100:101]
	global_load_lds_dwordx4 v5, s[100:101] offset:1024
	s_add_u32 s98, s98, 64
	s_addc_u32 s99, s99, 0
	s_add_u32 s100, s100, 64
	s_addc_u32 s101, s101, 0
	s_add_u32 s18, s16, 0x6000
	s_cmp_eq_u32 s18, 0x12000
	s_cselect_b32 s18, 0, s18
	s_add_u32 m0, s18, s17
	s_nop 0
	global_load_lds_dwordx4 v0, s[98:99]
	global_load_lds_dwordx4 v1, s[98:99] offset:1024
	global_load_lds_dwordx4 v2, s[100:101] offset:2048
	global_load_lds_dwordx4 v3, s[100:101] offset:3072
	s_add_u32 m0, m0, 0x1000
	s_nop 0
	global_load_lds_dwordx4 v4, s[100:101]
	global_load_lds_dwordx4 v5, s[100:101] offset:1024
	s_add_u32 s98, s98, 64
	s_addc_u32 s99, s99, 0
	s_add_u32 s100, s100, 64
	s_addc_u32 s101, s101, 0
	s_add_u32 s18, s18, 0x6000
	s_cmp_eq_u32 s18, 0x12000
	s_cselect_b32 s18, 0, s18
	s_add_u32 m0, s18, s17
	s_nop 0
	global_load_lds_dwordx4 v0, s[98:99]
	global_load_lds_dwordx4 v1, s[98:99] offset:1024
	global_load_lds_dwordx4 v2, s[100:101] offset:2048
	global_load_lds_dwordx4 v3, s[100:101] offset:3072
	s_add_u32 m0, m0, 0x1000
	s_nop 0
	global_load_lds_dwordx4 v4, s[100:101]
	global_load_lds_dwordx4 v5, s[100:101] offset:1024
	s_add_u32 s98, s98, 64
	s_addc_u32 s99, s99, 0
	s_add_u32 s100, s100, 64
	s_addc_u32 s101, s101, 0
.Lg778_entry:
	s_mov_b32 s15, 0
	s_waitcnt vmcnt(0)
	s_barrier
	v_add_u32_e32 v8, s16, v6
	v_add_u32_e32 v9, s16, v7
	ds_read_b128 v[172:175], v9
	ds_read_b128 v[176:179], v9 offset:1024
	ds_read_b128 v[180:183], v9 offset:2048
	ds_read_b128 v[184:187], v9 offset:3072
	ds_read_b128 v[10:13], v8
	ds_read_b128 v[14:17], v8 offset:1024
	ds_read_b128 v[18:21], v8 offset:6144
	ds_read_b128 v[152:155], v8 offset:7168
	ds_read_b128 v[192:195], v9 offset:6144
	ds_read_b128 v[196:199], v9 offset:7168
	ds_read_b128 v[200:203], v9 offset:8192
	ds_read_b128 v[204:207], v9 offset:9216
.Lg778_top:
	s_waitcnt lgkmcnt(4)
	v_mfma_f32_16x16x32_bf16 v[148:151], v[172:175], v[10:13], v[148:151]
	v_mfma_f32_16x16x32_bf16 v[116:119], v[172:175], v[14:17], v[116:119]
	v_mfma_f32_16x16x32_bf16 v[84:87], v[172:175], v[18:21], v[84:87]
	v_mfma_f32_16x16x32_bf16 v[52:55], v[172:175], v[152:155], v[52:55]
	v_mfma_f32_16x16x32_bf16 v[144:147], v[176:179], v[10:13], v[144:147]
	v_mfma_f32_16x16x32_bf16 v[112:115], v[176:179], v[14:17], v[112:115]
	v_mfma_f32_16x16x32_bf16 v[80:83], v[176:179], v[18:21], v[80:83]
	v_mfma_f32_16x16x32_bf16 v[48:51], v[176:179], v[152:155], v[48:51]
	v_mfma_f32_16x16x32_bf16 v[140:143], v[180:183], v[10:13], v[140:143]
	v_mfma_f32_16x16x32_bf16 v[108:111], v[180:183], v[14:17], v[108:111]
	v_mfma_f32_16x16x32_bf16 v[76:79], v[180:183], v[18:21], v[76:79]
	v_mfma_f32_16x16x32_bf16 v[44:47], v[180:183], v[152:155], v[44:47]
	v_mfma_f32_16x16x32_bf16 v[136:139], v[184:187], v[10:13], v[136:139]
	v_mfma_f32_16x16x32_bf16 v[104:107], v[184:187], v[14:17], v[104:107]
	v_mfma_f32_16x16x32_bf16 v[72:75], v[184:187], v[18:21], v[72:75]
	v_mfma_f32_16x16x32_bf16 v[40:43], v[184:187], v[152:155], v[40:43]
	s_waitcnt vmcnt(6)
	s_waitcnt lgkmcnt(0)
	s_barrier
	s_add_u32 s18, s16, 0x6000
	s_cmp_eq_u32 s18, 0x12000
	s_cselect_b32 s18, 0, s18
	v_add_u32_e32 v8, s18, v6
	v_add_u32_e32 v9, s18, v7
	ds_read_b128 v[172:175], v9
	ds_read_b128 v[176:179], v9 offset:1024
	ds_read_b128 v[180:183], v9 offset:2048
	ds_read_b128 v[184:187], v9 offset:3072
	s_cmp_eq_u32 s15, 29
	s_cbranch_scc1 .Lg778_sw
; DI f32x4 mfma(bf16x8 a, bf16x8 b, f32x4 c) { return __builtin_amdgcn_mfma_f32_16x16x32_bf16(a, b, c, 0, 0, 0); }
; #define G_LOAD(PA, PB, STEP) do { _Pragma("unroll") for (int i_ = 0; i_ < 2; ++i_) ra[i_] = *(const u32x4*)((PA) + (size_t)(64 * i_) * K + (STEP) * 32); \
;         _Pragma("unroll") for (int i_ = 0; i_ < 4; ++i_) rb[i_] = *(const u32x4*)((PB) + (size_t)(64 * i_) * K + (STEP) * 32); } while (0)
; #define G_STORE(BUF) do { _Pragma("unroll") for (int i_ = 0; i_ < 2; ++i_) *(u32x4*)(sA + (BUF) * 128 * 40 + (lrow + 64 * i_) * 40 + lcc * 8) = ra[i_]; \
;         _Pragma("unroll") for (int i_ = 0; i_ < 4; ++i_) *(u32x4*)(sB + (BUF) * 256 * 40 + (lrow + 64 * i_) * 40 + lcc * 8) = rb[i_]; } while (0)
; template <int EPI> ...
;     ...
;         for (int kt = 0; kt < nk; ++kt) {
;             const int buf = kt & 1;
;             const bf16_t* a_ = sA + buf * 128 * 40 + (wr * 64 + fr) * 40 + fq * 8;
;             const bf16_t* b_ = sB + buf * 256 * 40 + (wc * 128 + fr) * 40 + fq * 8;
;             bf16x8 af[4];
; #pragma unroll
;             for (int i = 0; i < 4; ++i) af[i] = *(const bf16x8*)(a_ + i * 16 * 40);
; #pragma unroll
;             for (int jh = 0; jh < 2; ++jh) {
;                 bf16x8 bfr[4];
; #pragma unroll
;                 for (int j = 0; j < 4; ++j) bfr[j] = *(const bf16x8*)(b_ + (jh * 4 + j) * 16 * 40);
; #pragma unroll
;                 for (int i = 0; i < 4; ++i)
; #pragma unroll
;                     for (int j = 0; j < 4; ++j) acc[i][jh * 4 + j] = mfma(bfr[j], af[i], acc[i][jh * 4 + j]);
;             }
;             G_STORE(buf ^ 1);
;             {
;                 const bool cur = kt + 2 < nk;
;                 const bf16_t* pa = cur ? Ag : An; const bf16_t* pb = cur ? Bg : Bn;
;                 const int st = cur ? kt + 2 : kt + 2 - nk;
;                 G_LOAD(pa, pb, st);
;             }
;             __syncthreads();
;         }
;     ...
; #pragma unroll
;         for (int i = 0; i < 4; ++i) {
;             const int m = mt * 128 + wr * 64 + i * 16 + fr;
;             float rsc = 1.f;
;             if (EPI != 2 && rs_in) rsc = rsqrtf(rs_in[m] * (1.f / DM) + 1e-6f);
.Lg778_swret:
	s_add_u32 m0, s16, s17
	v_mfma_f32_16x16x32_bf16 v[132:135], v[192:195], v[10:13], v[132:135]
	global_load_lds_dwordx4 v0, s[98:99]
	v_mfma_f32_16x16x32_bf16 v[128:131], v[196:199], v[10:13], v[128:131]
	v_mfma_f32_16x16x32_bf16 v[124:127], v[200:203], v[10:13], v[124:127]
	global_load_lds_dwordx4 v1, s[98:99] offset:1024
	v_mfma_f32_16x16x32_bf16 v[120:123], v[204:207], v[10:13], v[120:123]
	ds_read_b128 v[10:13], v8
	v_mfma_f32_16x16x32_bf16 v[100:103], v[192:195], v[14:17], v[100:103]
	global_load_lds_dwordx4 v2, s[100:101] offset:2048
	v_mfma_f32_16x16x32_bf16 v[96:99], v[196:199], v[14:17], v[96:99]
	v_mfma_f32_16x16x32_bf16 v[92:95], v[200:203], v[14:17], v[92:95]
	global_load_lds_dwordx4 v3, s[100:101] offset:3072
	v_mfma_f32_16x16x32_bf16 v[88:91], v[204:207], v[14:17], v[88:91]
	ds_read_b128 v[14:17], v8 offset:1024
	v_mfma_f32_16x16x32_bf16 v[68:71], v[192:195], v[18:21], v[68:71]
	s_add_u32 m0, m0, 0x1000
	v_mfma_f32_16x16x32_bf16 v[64:67], v[196:199], v[18:21], v[64:67]
	global_load_lds_dwordx4 v4, s[100:101]
	v_mfma_f32_16x16x32_bf16 v[60:63], v[200:203], v[18:21], v[60:63]
	v_mfma_f32_16x16x32_bf16 v[56:59], v[204:207], v[18:21], v[56:59]
	ds_read_b128 v[18:21], v8 offset:6144
	v_mfma_f32_16x16x32_bf16 v[36:39], v[192:195], v[152:155], v[36:39]
	global_load_lds_dwordx4 v5, s[100:101] offset:1024
	v_mfma_f32_16x16x32_bf16 v[32:35], v[196:199], v[152:155], v[32:35]
	v_mfma_f32_16x16x32_bf16 v[28:31], v[200:203], v[152:155], v[28:31]
	v_mfma_f32_16x16x32_bf16 v[24:27], v[204:207], v[152:155], v[24:27]
	ds_read_b128 v[152:155], v8 offset:7168
	ds_read_b128 v[192:195], v9 offset:6144
	ds_read_b128 v[196:199], v9 offset:7168
	ds_read_b128 v[200:203], v9 offset:8192
	ds_read_b128 v[204:207], v9 offset:9216
	s_add_u32 s98, s98, 64
	s_addc_u32 s99, s99, 0
	s_add_u32 s100, s100, 64
	s_addc_u32 s101, s101, 0
	s_add_u32 s16, s16, 0x6000
	s_cmp_eq_u32 s16, 0x12000
	s_cselect_b32 s16, 0, s16
	s_add_u32 s15, s15, 1
	s_cmp_lt_u32 s15, 31
	s_cbranch_scc1 .Lg778_top
	s_waitcnt lgkmcnt(4)
	v_mfma_f32_16x16x32_bf16 v[148:151], v[172:175], v[10:13], v[148:151]
	v_mfma_f32_16x16x32_bf16 v[116:119], v[172:175], v[14:17], v[116:119]
	v_mfma_f32_16x16x32_bf16 v[84:87], v[172:175], v[18:21], v[84:87]
	v_mfma_f32_16x16x32_bf16 v[52:55], v[172:175], v[152:155], v[52:55]
	v_mfma_f32_16x16x32_bf16 v[144:147], v[176:179], v[10:13], v[144:147]
	v_mfma_f32_16x16x32_bf16 v[112:115], v[176:179], v[14:17], v[112:115]
	v_mfma_f32_16x16x32_bf16 v[80:83], v[176:179], v[18:21], v[80:83]
	v_mfma_f32_16x16x32_bf16 v[48:51], v[176:179], v[152:155], v[48:51]
	v_mfma_f32_16x16x32_bf16 v[140:143], v[180:183], v[10:13], v[140:143]
	v_mfma_f32_16x16x32_bf16 v[108:111], v[180:183], v[14:17], v[108:111]
	v_mfma_f32_16x16x32_bf16 v[76:79], v[180:183], v[18:21], v[76:79]
	v_mfma_f32_16x16x32_bf16 v[44:47], v[180:183], v[152:155], v[44:47]
	v_mfma_f32_16x16x32_bf16 v[136:139], v[184:187], v[10:13], v[136:139]
	v_mfma_f32_16x16x32_bf16 v[104:107], v[184:187], v[14:17], v[104:107]
	v_mfma_f32_16x16x32_bf16 v[72:75], v[184:187], v[18:21], v[72:75]
	v_mfma_f32_16x16x32_bf16 v[40:43], v[184:187], v[152:155], v[40:43]
	s_waitcnt vmcnt(6)
	s_waitcnt lgkmcnt(0)
	s_barrier
	s_add_u32 m0, s16, s17
	v_mfma_f32_16x16x32_bf16 v[132:135], v[192:195], v[10:13], v[132:135]
	global_load_lds_dwordx4 v0, s[98:99]
	v_mfma_f32_16x16x32_bf16 v[128:131], v[196:199], v[10:13], v[128:131]
	v_mfma_f32_16x16x32_bf16 v[124:127], v[200:203], v[10:13], v[124:127]
	global_load_lds_dwordx4 v1, s[98:99] offset:1024
	v_mfma_f32_16x16x32_bf16 v[120:123], v[204:207], v[10:13], v[120:123]
	v_mfma_f32_16x16x32_bf16 v[100:103], v[192:195], v[14:17], v[100:103]
	global_load_lds_dwordx4 v2, s[100:101] offset:2048
	v_mfma_f32_16x16x32_bf16 v[96:99], v[196:199], v[14:17], v[96:99]
	v_mfma_f32_16x16x32_bf16 v[92:95], v[200:203], v[14:17], v[92:95]
	global_load_lds_dwordx4 v3, s[100:101] offset:3072
	v_mfma_f32_16x16x32_bf16 v[88:91], v[204:207], v[14:17], v[88:91]
	v_mfma_f32_16x16x32_bf16 v[68:71], v[192:195], v[18:21], v[68:71]
	s_add_u32 m0, m0, 0x1000
	v_mfma_f32_16x16x32_bf16 v[64:67], v[196:199], v[18:21], v[64:67]
	global_load_lds_dwordx4 v4, s[100:101]
	v_mfma_f32_16x16x32_bf16 v[60:63], v[200:203], v[18:21], v[60:63]
	v_mfma_f32_16x16x32_bf16 v[56:59], v[204:207], v[18:21], v[56:59]
	v_mfma_f32_16x16x32_bf16 v[36:39], v[192:195], v[152:155], v[36:39]
	global_load_lds_dwordx4 v5, s[100:101] offset:1024
	v_mfma_f32_16x16x32_bf16 v[32:35], v[196:199], v[152:155], v[32:35]
	v_mfma_f32_16x16x32_bf16 v[28:31], v[200:203], v[152:155], v[28:31]
	v_mfma_f32_16x16x32_bf16 v[24:27], v[204:207], v[152:155], v[24:27]
	s_add_u32 s98, s98, 64
	s_addc_u32 s99, s99, 0
	s_add_u32 s100, s100, 64
	s_addc_u32 s101, s101, 0
	s_add_u32 s16, s16, 0x6000
	s_cmp_eq_u32 s16, 0x12000
	s_cselect_b32 s16, 0, s16
	s_add_u32 s15, s15, 1
	s_branch .Lg778_end
.Lg778_sw:
	v_readlane_b32 vcc_lo, v253, 0
	v_readlane_b32 vcc_hi, v253, 1
	s_lshl_b32 s18, s13, 18
	s_nop 1
	s_add_u32 s98, vcc_lo, s18
	s_addc_u32 s99, vcc_hi, 0
	s_sub_u32 s98, s98, 0x1000
	s_subb_u32 s99, s99, 0
	v_readlane_b32 vcc_lo, v253, 2
	v_readlane_b32 vcc_hi, v253, 3
	s_lshl_b32 s18, s14, 19
	s_nop 1
	s_add_u32 s100, vcc_lo, s18
	s_addc_u32 s101, vcc_hi, 0
	s_sub_u32 s100, s100, 0x1000
	s_subb_u32 s101, s101, 0
	s_branch .Lg778_swret
.Lg778_end:
	v_writelane_b32 v253, s16, 4
	v_lshl_add_u32 v154, s7, 7, v167
	v_ashrrev_i32_e32 v155, 31, v154
	v_mov_b32_e32 v162, 1.0
	s_and_b64 vcc, exec, s[20:21]
	v_lshl_add_u64 v[160:161], v[154:155], 2, s[10:11]
	v_mov_b32_e32 v164, 1.0
	s_cbranch_vccz .LBB0_781
	global_load_dword v152, v[160:161], off
	s_waitcnt vmcnt(0)
	v_fmamk_f32 v152, v152, 0x3a800000, v212
	v_mul_f32_e32 v153, 0x4b800000, v152
	v_cmp_gt_f32_e32 vcc, s28, v152
	s_nop 1
	v_cndmask_b32_e32 v152, v152, v153, vcc
	v_rsq_f32_e32 v152, v152
	s_nop 0
	v_mul_f32_e32 v153, 0x45800000, v152
	v_cndmask_b32_e32 v164, v152, v153, vcc

; template <int EPI> ...
;     ...
;     const int idx0 = blockIdx.x >> 3;
;     if (idx0 < perX) {
;         int mt0, nt0; tile_of(idx0, mt0, nt0);
;         const bf16_t* A0 = A + (size_t)(mt0 * 128 + lrow) * K + lcc * 8;
;         const bf16_t* B0 = Bt + (size_t)(nt0 * 256 + lrowp) * K + lcc * 8;
;         G_LOAD(A0, B0, 0);
;         G_STORE(0);
;         G_LOAD(A0, B0, 1);
;         __syncthreads();
;     }
;     for (int idx = idx0; idx < perX; idx += nbx) {
;         int mt, nt; tile_of(idx, mt, nt);
;         int mtn, ntn; tile_of(idx + nbx < perX ? idx + nbx : idx, mtn, ntn);
;         const bf16_t* Ag = A + (size_t)(mt * 128 + lrow) * K + lcc * 8;
;         const bf16_t* Bg = Bt + (size_t)(nt * 256 + lrowp) * K + lcc * 8;
;         const bf16_t* An = A + (size_t)(mtn * 128 + lrow) * K + lcc * 8;
;         const bf16_t* Bn = Bt + (size_t)(ntn * 256 + lrowp) * K + lcc * 8;
;         f32x4 acc[4][8];
; #pragma unroll
;         for (int i = 0; i < 4; ++i)
; #pragma unroll
;             for (int j = 0; j < 8; ++j) {
;                 if (EPI == 2)
;                     acc[i][j] = *(const f32x4*)(xin + (size_t)(mt * 128 + wr * 64 + i * 16 + fr) * Nn + nt * 256 + wc * 128 + 32 * (j >> 1) + 8 * fq + 4 * (j & 1));
;                 else acc[i][j] = (f32x4){0.f, 0.f, 0.f, 0.f};
;             }
;         for (int kt = 0; kt < nk; ++kt) {
;             const int buf = kt & 1;
;             const bf16_t* a_ = sA + buf * 128 * 40 + (wr * 64 + fr) * 40 + fq * 8;
;             const bf16_t* b_ = sB + buf * 256 * 40 + (wc * 128 + fr) * 40 + fq * 8;
;             bf16x8 af[4];
; #pragma unroll
;             for (int i = 0; i < 4; ++i) af[i] = *(const bf16x8*)(a_ + i * 16 * 40);
; #pragma unroll
;             for (int jh = 0; jh < 2; ++jh) {
;                 bf16x8 bfr[4];
; #pragma unroll
;                 for (int j = 0; j < 4; ++j) bfr[j] = *(const bf16x8*)(b_ + (jh * 4 + j) * 16 * 40);
; #pragma unroll
;                 for (int i = 0; i < 4; ++i)
; #pragma unroll
;                     for (int j = 0; j < 4; ++j) acc[i][jh * 4 + j] = mfma(bfr[j], af[i], acc[i][jh * 4 + j]);
;             }
;             G_STORE(buf ^ 1);
;             {
;                 const bool cur = kt + 2 < nk;
;                 const bf16_t* pa = cur ? Ag : An; const bf16_t* pb = cur ? Bg : Bn;
;                 const int st = cur ? kt + 2 : kt + 2 - nk;
;                 G_LOAD(pa, pb, st);
.LBB0_843:
	v_readlane_b32 s15, v253, 4
	v_readlane_b32 s16, v253, 6
	v_readlane_b32 s17, v253, 5
	s_nop 3
	s_cmp_eq_u32 s17, 0
	s_cbranch_scc1 .Lg843_entry
	v_and_b32_e32 v8, 63, v210
	v_lshrrev_b32_e32 v9, 6, v210
	s_nop 0
	v_readfirstlane_b32 s17, v9
	v_lshrrev_b32_e32 v9, 4, v8
	v_sub_u32_e32 v10, 0, v9
	v_and_b32_e32 v10, 3, v10
	v_and_b32_e32 v11, 3, v8
	v_xor_b32_e32 v11, v11, v10
	v_lshrrev_b32_e32 v12, 2, v8
	v_lshlrev_b32_e32 v0, 13, v12
	v_lshl_add_u32 v0, v11, 4, v0
	s_lshl_b32 vcc_lo, s17, 18
	v_add_u32_e32 v0, vcc_lo, v0
	v_add_u32_e32 v0, 0x1000, v0
	v_add_u32_e32 v1, 0x1fc00, v0
	v_and_b32_e32 v13, 3, v12
	v_lshl_add_u32 v13, v9, 3, v13
	v_lshlrev_b32_e32 v2, 13, v13
	v_lshl_add_u32 v2, v11, 4, v2
	s_lshl_b32 vcc_lo, s17, 19
	v_add_u32_e32 v2, vcc_lo, v2
	v_add_u32_e32 v2, 0x800, v2
	v_add_u32_e32 v3, 0x7c00, v2
	v_add_u32_e32 v4, 0x40800, v2
	v_add_u32_e32 v5, 0x48400, v2
	v_and_b32_e32 v10, 15, v8
	v_lshrrev_b32_e32 v11, 2, v10
	v_sub_u32_e32 v11, 0, v11
	v_and_b32_e32 v11, 3, v11
	v_xor_b32_e32 v11, v9, v11
	v_lshlrev_b32_e32 v6, 6, v10
	v_lshl_add_u32 v6, v11, 4, v6
	s_lshr_b32 vcc_lo, s17, 1
	s_mul_i32 vcc_lo, vcc_lo, 0x3000
	s_and_b32 vcc_hi, s17, 1
	s_mul_i32 vcc_hi, vcc_hi, 0x3000
	s_add_u32 vcc_hi, vcc_hi, 0x800
	v_add_u32_e32 v7, vcc_hi, v6
	v_add_u32_e32 v6, vcc_lo, v6
	s_mul_i32 s16, s17, 0x1800
	v_writelane_b32 v253, s16, 6
	v_writelane_b32 v253, 0, 5
	v_readlane_b32 vcc_lo, v253, 0
	v_readlane_b32 vcc_hi, v253, 1
	s_lshl_b32 s17, s9, 20
	s_nop 1
	s_add_u32 s98, vcc_lo, s17
	s_addc_u32 s99, vcc_hi, 0
	s_sub_u32 s98, s98, 0x1000
	s_subb_u32 s99, s99, 0
	v_readlane_b32 vcc_lo, v253, 2
	v_readlane_b32 vcc_hi, v253, 3
	s_lshl_b32 s17, s10, 21
	s_nop 1
	s_add_u32 s100, vcc_lo, s17
	s_addc_u32 s101, vcc_hi, 0
	s_sub_u32 s100, s100, 0x1000
	s_subb_u32 s101, s101, 0
	s_add_u32 m0, s15, s16
	s_nop 0
	global_load_lds_dwordx4 v0, s[98:99]
	global_load_lds_dwordx4 v1, s[98:99] offset:1024
	global_load_lds_dwordx4 v2, s[100:101] offset:2048
	global_load_lds_dwordx4 v3, s[100:101] offset:3072
	s_add_u32 m0, m0, 0x1000
	s_nop 0
	global_load_lds_dwordx4 v4, s[100:101]
	global_load_lds_dwordx4 v5, s[100:101] offset:1024
	s_add_u32 s98, s98, 64
	s_addc_u32 s99, s99, 0
	s_add_u32 s100, s100, 64
	s_addc_u32 s101, s101, 0
	s_add_u32 s17, s15, 0x6000
	s_cmp_eq_u32 s17, 0x12000
	s_cselect_b32 s17, 0, s17
	s_add_u32 m0, s17, s16
	s_nop 0
	global_load_lds_dwordx4 v0, s[98:99]
	global_load_lds_dwordx4 v1, s[98:99] offset:1024
	global_load_lds_dwordx4 v2, s[100:101] offset:2048
	global_load_lds_dwordx4 v3, s[100:101] offset:3072
	s_add_u32 m0, m0, 0x1000
	s_nop 0
	global_load_lds_dwordx4 v4, s[100:101]
	global_load_lds_dwordx4 v5, s[100:101] offset:1024
	s_add_u32 s98, s98, 64
	s_addc_u32 s99, s99, 0
	s_add_u32 s100, s100, 64
	s_addc_u32 s101, s101, 0
	s_add_u32 s17, s17, 0x6000
	s_cmp_eq_u32 s17, 0x12000
	s_cselect_b32 s17, 0, s17
	s_add_u32 m0, s17, s16
	s_nop 0
	global_load_lds_dwordx4 v0, s[98:99]
	global_load_lds_dwordx4 v1, s[98:99] offset:1024
	global_load_lds_dwordx4 v2, s[100:101] offset:2048
	global_load_lds_dwordx4 v3, s[100:101] offset:3072
	s_add_u32 m0, m0, 0x1000
	s_nop 0
	global_load_lds_dwordx4 v4, s[100:101]
	global_load_lds_dwordx4 v5, s[100:101] offset:1024
	s_add_u32 s98, s98, 64
	s_addc_u32 s99, s99, 0
	s_add_u32 s100, s100, 64
	s_addc_u32 s101, s101, 0
.Lg843_entry:
	s_mov_b32 s14, 0
	s_waitcnt vmcnt(0)
	s_barrier
	v_add_u32_e32 v8, s15, v6
	v_add_u32_e32 v9, s15, v7
	ds_read_b128 v[174:177], v9
	ds_read_b128 v[178:181], v9 offset:1024
	ds_read_b128 v[182:185], v9 offset:2048
	ds_read_b128 v[192:195], v9 offset:3072
	ds_read_b128 v[10:13], v8
	ds_read_b128 v[14:17], v8 offset:1024
	ds_read_b128 v[18:21], v8 offset:6144
	ds_read_b128 v[154:157], v8 offset:7168
	ds_read_b128 v[196:199], v9 offset:6144
	ds_read_b128 v[200:203], v9 offset:7168
	ds_read_b128 v[204:207], v9 offset:8192
	ds_read_b128 v[232:235], v9 offset:9216
.Lg843_top:
	s_waitcnt lgkmcnt(4)
	v_mfma_f32_16x16x32_bf16 v[148:151], v[174:177], v[10:13], v[148:151]
	v_mfma_f32_16x16x32_bf16 v[116:119], v[174:177], v[14:17], v[116:119]
	v_mfma_f32_16x16x32_bf16 v[84:87], v[174:177], v[18:21], v[84:87]
	v_mfma_f32_16x16x32_bf16 v[52:55], v[174:177], v[154:157], v[52:55]
	v_mfma_f32_16x16x32_bf16 v[144:147], v[178:181], v[10:13], v[144:147]
	v_mfma_f32_16x16x32_bf16 v[112:115], v[178:181], v[14:17], v[112:115]
	v_mfma_f32_16x16x32_bf16 v[80:83], v[178:181], v[18:21], v[80:83]
	v_mfma_f32_16x16x32_bf16 v[48:51], v[178:181], v[154:157], v[48:51]
	v_mfma_f32_16x16x32_bf16 v[140:143], v[182:185], v[10:13], v[140:143]
	v_mfma_f32_16x16x32_bf16 v[108:111], v[182:185], v[14:17], v[108:111]
	v_mfma_f32_16x16x32_bf16 v[76:79], v[182:185], v[18:21], v[76:79]
	v_mfma_f32_16x16x32_bf16 v[44:47], v[182:185], v[154:157], v[44:47]
	v_mfma_f32_16x16x32_bf16 v[136:139], v[192:195], v[10:13], v[136:139]
	v_mfma_f32_16x16x32_bf16 v[104:107], v[192:195], v[14:17], v[104:107]
	v_mfma_f32_16x16x32_bf16 v[72:75], v[192:195], v[18:21], v[72:75]
	v_mfma_f32_16x16x32_bf16 v[40:43], v[192:195], v[154:157], v[40:43]
	s_waitcnt vmcnt(6)
	s_waitcnt lgkmcnt(0)
	s_barrier
	s_add_u32 s17, s15, 0x6000
	s_cmp_eq_u32 s17, 0x12000
	s_cselect_b32 s17, 0, s17
	v_add_u32_e32 v8, s17, v6
	v_add_u32_e32 v9, s17, v7
	ds_read_b128 v[174:177], v9
	ds_read_b128 v[178:181], v9 offset:1024
	ds_read_b128 v[182:185], v9 offset:2048
	ds_read_b128 v[192:195], v9 offset:3072
	s_cmp_eq_u32 s14, 125
	s_cbranch_scc1 .Lg843_sw
; DI f32x4 mfma(bf16x8 a, bf16x8 b, f32x4 c) { return __builtin_amdgcn_mfma_f32_16x16x32_bf16(a, b, c, 0, 0, 0); }
; #define G_LOAD(PA, PB, STEP) do { _Pragma("unroll") for (int i_ = 0; i_ < 2; ++i_) ra[i_] = *(const u32x4*)((PA) + (size_t)(64 * i_) * K + (STEP) * 32); \
;         _Pragma("unroll") for (int i_ = 0; i_ < 4; ++i_) rb[i_] = *(const u32x4*)((PB) + (size_t)(64 * i_) * K + (STEP) * 32); } while (0)
; #define G_STORE(BUF) do { _Pragma("unroll") for (int i_ = 0; i_ < 2; ++i_) *(u32x4*)(sA + (BUF) * 128 * 40 + (lrow + 64 * i_) * 40 + lcc * 8) = ra[i_]; \
;         _Pragma("unroll") for (int i_ = 0; i_ < 4; ++i_) *(u32x4*)(sB + (BUF) * 256 * 40 + (lrow + 64 * i_) * 40 + lcc * 8) = rb[i_]; } while (0)
; template <int EPI> ...
;     ...
;         for (int kt = 0; kt < nk; ++kt) {
;             const int buf = kt & 1;
;             const bf16_t* a_ = sA + buf * 128 * 40 + (wr * 64 + fr) * 40 + fq * 8;
;             const bf16_t* b_ = sB + buf * 256 * 40 + (wc * 128 + fr) * 40 + fq * 8;
;             bf16x8 af[4];
; #pragma unroll
;             for (int i = 0; i < 4; ++i) af[i] = *(const bf16x8*)(a_ + i * 16 * 40);
; #pragma unroll
;             for (int jh = 0; jh < 2; ++jh) {
;                 bf16x8 bfr[4];
; #pragma unroll
;                 for (int j = 0; j < 4; ++j) bfr[j] = *(const bf16x8*)(b_ + (jh * 4 + j) * 16 * 40);
; #pragma unroll
;                 for (int i = 0; i < 4; ++i)
; #pragma unroll
;                     for (int j = 0; j < 4; ++j) acc[i][jh * 4 + j] = mfma(bfr[j], af[i], acc[i][jh * 4 + j]);
;             }
;             G_STORE(buf ^ 1);
;             {
;                 const bool cur = kt + 2 < nk;
;                 const bf16_t* pa = cur ? Ag : An; const bf16_t* pb = cur ? Bg : Bn;
;                 const int st = cur ? kt + 2 : kt + 2 - nk;
;                 G_LOAD(pa, pb, st);
;             }
;             __syncthreads();
;         }
.Lg843_swret:
	s_add_u32 m0, s15, s16
	v_mfma_f32_16x16x32_bf16 v[132:135], v[196:199], v[10:13], v[132:135]
	global_load_lds_dwordx4 v0, s[98:99]
	v_mfma_f32_16x16x32_bf16 v[128:131], v[200:203], v[10:13], v[128:131]
	v_mfma_f32_16x16x32_bf16 v[124:127], v[204:207], v[10:13], v[124:127]
	global_load_lds_dwordx4 v1, s[98:99] offset:1024
	v_mfma_f32_16x16x32_bf16 v[120:123], v[232:235], v[10:13], v[120:123]
	ds_read_b128 v[10:13], v8
	v_mfma_f32_16x16x32_bf16 v[100:103], v[196:199], v[14:17], v[100:103]
	global_load_lds_dwordx4 v2, s[100:101] offset:2048
	v_mfma_f32_16x16x32_bf16 v[96:99], v[200:203], v[14:17], v[96:99]
	v_mfma_f32_16x16x32_bf16 v[92:95], v[204:207], v[14:17], v[92:95]
	global_load_lds_dwordx4 v3, s[100:101] offset:3072
	v_mfma_f32_16x16x32_bf16 v[88:91], v[232:235], v[14:17], v[88:91]
	ds_read_b128 v[14:17], v8 offset:1024
	v_mfma_f32_16x16x32_bf16 v[68:71], v[196:199], v[18:21], v[68:71]
	s_add_u32 m0, m0, 0x1000
	v_mfma_f32_16x16x32_bf16 v[64:67], v[200:203], v[18:21], v[64:67]
	global_load_lds_dwordx4 v4, s[100:101]
	v_mfma_f32_16x16x32_bf16 v[60:63], v[204:207], v[18:21], v[60:63]
	v_mfma_f32_16x16x32_bf16 v[56:59], v[232:235], v[18:21], v[56:59]
	ds_read_b128 v[18:21], v8 offset:6144
	v_mfma_f32_16x16x32_bf16 v[36:39], v[196:199], v[154:157], v[36:39]
	global_load_lds_dwordx4 v5, s[100:101] offset:1024
	v_mfma_f32_16x16x32_bf16 v[32:35], v[200:203], v[154:157], v[32:35]
	v_mfma_f32_16x16x32_bf16 v[28:31], v[204:207], v[154:157], v[28:31]
	v_mfma_f32_16x16x32_bf16 v[24:27], v[232:235], v[154:157], v[24:27]
	ds_read_b128 v[154:157], v8 offset:7168
	ds_read_b128 v[196:199], v9 offset:6144
	ds_read_b128 v[200:203], v9 offset:7168
	ds_read_b128 v[204:207], v9 offset:8192
	ds_read_b128 v[232:235], v9 offset:9216
	s_add_u32 s98, s98, 64
	s_addc_u32 s99, s99, 0
	s_add_u32 s100, s100, 64
	s_addc_u32 s101, s101, 0
	s_add_u32 s15, s15, 0x6000
	s_cmp_eq_u32 s15, 0x12000
	s_cselect_b32 s15, 0, s15
	s_add_u32 s14, s14, 1
	s_cmp_lt_u32 s14, 127
	s_cbranch_scc1 .Lg843_top
	s_waitcnt lgkmcnt(4)
	v_mfma_f32_16x16x32_bf16 v[148:151], v[174:177], v[10:13], v[148:151]
	v_mfma_f32_16x16x32_bf16 v[116:119], v[174:177], v[14:17], v[116:119]
	v_mfma_f32_16x16x32_bf16 v[84:87], v[174:177], v[18:21], v[84:87]
	v_mfma_f32_16x16x32_bf16 v[52:55], v[174:177], v[154:157], v[52:55]
	v_mfma_f32_16x16x32_bf16 v[144:147], v[178:181], v[10:13], v[144:147]
	v_mfma_f32_16x16x32_bf16 v[112:115], v[178:181], v[14:17], v[112:115]
	v_mfma_f32_16x16x32_bf16 v[80:83], v[178:181], v[18:21], v[80:83]
	v_mfma_f32_16x16x32_bf16 v[48:51], v[178:181], v[154:157], v[48:51]
	v_mfma_f32_16x16x32_bf16 v[140:143], v[182:185], v[10:13], v[140:143]
	v_mfma_f32_16x16x32_bf16 v[108:111], v[182:185], v[14:17], v[108:111]
	v_mfma_f32_16x16x32_bf16 v[76:79], v[182:185], v[18:21], v[76:79]
	v_mfma_f32_16x16x32_bf16 v[44:47], v[182:185], v[154:157], v[44:47]
	v_mfma_f32_16x16x32_bf16 v[136:139], v[192:195], v[10:13], v[136:139]
	v_mfma_f32_16x16x32_bf16 v[104:107], v[192:195], v[14:17], v[104:107]
	v_mfma_f32_16x16x32_bf16 v[72:75], v[192:195], v[18:21], v[72:75]
	v_mfma_f32_16x16x32_bf16 v[40:43], v[192:195], v[154:157], v[40:43]
	s_waitcnt vmcnt(6)
	s_waitcnt lgkmcnt(0)
	s_barrier
	s_add_u32 m0, s15, s16
	v_mfma_f32_16x16x32_bf16 v[132:135], v[196:199], v[10:13], v[132:135]
	global_load_lds_dwordx4 v0, s[98:99]
	v_mfma_f32_16x16x32_bf16 v[128:131], v[200:203], v[10:13], v[128:131]
	v_mfma_f32_16x16x32_bf16 v[124:127], v[204:207], v[10:13], v[124:127]
	global_load_lds_dwordx4 v1, s[98:99] offset:1024
	v_mfma_f32_16x16x32_bf16 v[120:123], v[232:235], v[10:13], v[120:123]
	v_mfma_f32_16x16x32_bf16 v[100:103], v[196:199], v[14:17], v[100:103]
	global_load_lds_dwordx4 v2, s[100:101] offset:2048
	v_mfma_f32_16x16x32_bf16 v[96:99], v[200:203], v[14:17], v[96:99]
	v_mfma_f32_16x16x32_bf16 v[92:95], v[204:207], v[14:17], v[92:95]
	global_load_lds_dwordx4 v3, s[100:101] offset:3072
	v_mfma_f32_16x16x32_bf16 v[88:91], v[232:235], v[14:17], v[88:91]
	v_mfma_f32_16x16x32_bf16 v[68:71], v[196:199], v[18:21], v[68:71]
	s_add_u32 m0, m0, 0x1000
	v_mfma_f32_16x16x32_bf16 v[64:67], v[200:203], v[18:21], v[64:67]
	global_load_lds_dwordx4 v4, s[100:101]
	v_mfma_f32_16x16x32_bf16 v[60:63], v[204:207], v[18:21], v[60:63]
	v_mfma_f32_16x16x32_bf16 v[56:59], v[232:235], v[18:21], v[56:59]
	v_mfma_f32_16x16x32_bf16 v[36:39], v[196:199], v[154:157], v[36:39]
	global_load_lds_dwordx4 v5, s[100:101] offset:1024
	v_mfma_f32_16x16x32_bf16 v[32:35], v[200:203], v[154:157], v[32:35]
	v_mfma_f32_16x16x32_bf16 v[28:31], v[204:207], v[154:157], v[28:31]
	v_mfma_f32_16x16x32_bf16 v[24:27], v[232:235], v[154:157], v[24:27]
	s_add_u32 s98, s98, 64
	s_addc_u32 s99, s99, 0
	s_add_u32 s100, s100, 64
	s_addc_u32 s101, s101, 0
	s_add_u32 s15, s15, 0x6000
	s_cmp_eq_u32 s15, 0x12000
	s_cselect_b32 s15, 0, s15
	s_add_u32 s14, s14, 1
	s_branch .Lg843_end
; template <int EPI> ...
;     ...
;         int mtn, ntn; tile_of(idx + nbx < perX ? idx + nbx : idx, mtn, ntn);
;         const bf16_t* Ag = A + (size_t)(mt * 128 + lrow) * K + lcc * 8;
;         const bf16_t* Bg = Bt + (size_t)(nt * 256 + lrowp) * K + lcc * 8;
;         const bf16_t* An = A + (size_t)(mtn * 128 + lrow) * K + lcc * 8;
;         const bf16_t* Bn = Bt + (size_t)(ntn * 256 + lrowp) * K + lcc * 8;
;     ...
;                 } else {
;                     *(f32x4*)(xout + (size_t)m * Nn + n0) = v0;
;                     *(f32x4*)(xout + (size_t)m * Nn + n0 + 4) = v1;
.Lg843_sw:
	v_readlane_b32 vcc_lo, v253, 0
	v_readlane_b32 vcc_hi, v253, 1
	s_lshl_b32 s17, s12, 20
	s_nop 1
	s_add_u32 s98, vcc_lo, s17
	s_addc_u32 s99, vcc_hi, 0
	s_sub_u32 s98, s98, 0x1000
	s_subb_u32 s99, s99, 0
	v_readlane_b32 vcc_lo, v253, 2
	v_readlane_b32 vcc_hi, v253, 3
	s_lshl_b32 s17, s13, 21
	s_nop 1
	s_add_u32 s100, vcc_lo, s17
	s_addc_u32 s101, vcc_hi, 0
	s_sub_u32 s100, s100, 0x1000
	s_subb_u32 s101, s101, 0
	s_branch .Lg843_swret
.Lg843_end:
	v_writelane_b32 v253, s15, 4
	v_readlane_b32 s12, v251, 34
	v_readlane_b32 s13, v251, 35
	v_readlane_b32 s14, v251, 36
	v_readlane_b32 s15, v251, 37
	v_readlane_b32 s16, v251, 38
	v_readlane_b32 s17, v251, 39
	v_readlane_b32 s18, v251, 40
	v_readlane_b32 s19, v251, 41
	v_readlane_b32 s20, v251, 42
	v_readlane_b32 s21, v251, 43
	v_readlane_b32 s22, v251, 44
	v_readlane_b32 s23, v251, 45
	v_or_b32_e32 v173, s11, v172
	v_readlane_b32 s24, v251, 46
	v_readlane_b32 s25, v251, 47
	v_readlane_b32 s26, v251, 48
	v_readlane_b32 s27, v251, 49
	s_mov_b64 s[12:13], s[16:17]
	v_lshl_add_u64 v[164:165], s[12:13], 0, v[164:165]
	v_lshlrev_b32_e32 v188, 2, v173
	v_lshl_add_u64 v[164:165], v[164:165], 0, v[188:189]
	global_store_dwordx4 v[164:165], v[148:151], off
	global_store_dwordx4 v[164:165], v[144:147], off offset:16
	global_store_dwordx4 v[164:165], v[140:143], off offset:128
	global_store_dwordx4 v[164:165], v[136:139], off offset:144
	global_store_dwordx4 v[164:165], v[132:135], off offset:256
	global_store_dwordx4 v[164:165], v[128:131], off offset:272
	global_store_dwordx4 v[164:165], v[124:127], off offset:384
	global_store_dwordx4 v[164:165], v[120:123], off offset:400
	s_and_b64 vcc, exec, s[6:7]
	s_mov_b64 s[14:15], s[18:19]
	v_lshl_add_u64 v[120:121], s[12:13], 0, v[162:163]
	v_lshl_add_u64 v[120:121], v[120:121], 0, v[188:189]
	global_store_dwordx4 v[120:121], v[116:119], off
	global_store_dwordx4 v[120:121], v[112:115], off offset:16
	global_store_dwordx4 v[120:121], v[108:111], off offset:128
	global_store_dwordx4 v[120:121], v[104:107], off offset:144
	global_store_dwordx4 v[120:121], v[100:103], off offset:256
	global_store_dwordx4 v[120:121], v[96:99], off offset:272
	global_store_dwordx4 v[120:121], v[92:95], off offset:384
	global_store_dwordx4 v[120:121], v[88:91], off offset:400
	s_mov_b64 s[16:17], s[20:21]
	s_mov_b64 s[18:19], s[22:23]
	v_lshl_add_u64 v[88:89], s[12:13], 0, v[160:161]
	v_lshl_add_u64 v[88:89], v[88:89], 0, v[188:189]
	global_store_dwordx4 v[88:89], v[84:87], off
	global_store_dwordx4 v[88:89], v[80:83], off offset:16
	global_store_dwordx4 v[88:89], v[76:79], off offset:128
	global_store_dwordx4 v[88:89], v[72:75], off offset:144
	global_store_dwordx4 v[88:89], v[68:71], off offset:256
	global_store_dwordx4 v[88:89], v[64:67], off offset:272
	global_store_dwordx4 v[88:89], v[60:63], off offset:384
	global_store_dwordx4 v[88:89], v[56:59], off offset:400
	s_mov_b64 s[20:21], s[24:25]
	s_mov_b64 s[22:23], s[26:27]
	v_lshl_add_u64 v[56:57], s[12:13], 0, v[158:159]
	v_lshl_add_u64 v[56:57], v[56:57], 0, v[188:189]
	global_store_dwordx4 v[56:57], v[52:55], off
	global_store_dwordx4 v[56:57], v[48:51], off offset:16
	global_store_dwordx4 v[56:57], v[44:47], off offset:128
	global_store_dwordx4 v[56:57], v[40:43], off offset:144
	global_store_dwordx4 v[56:57], v[36:39], off offset:256
	global_store_dwordx4 v[56:57], v[32:35], off offset:272
	global_store_dwordx4 v[56:57], v[28:31], off offset:384
	global_store_dwordx4 v[56:57], v[24:27], off offset:400
	s_cbranch_vccz .LBB0_842

; template <int EPI> ...
;     ...
;     const int idx0 = blockIdx.x >> 3;
;     if (idx0 < perX) {
;         int mt0, nt0; tile_of(idx0, mt0, nt0);
;         const bf16_t* A0 = A + (size_t)(mt0 * 128 + lrow) * K + lcc * 8;
;         const bf16_t* B0 = Bt + (size_t)(nt0 * 256 + lrowp) * K + lcc * 8;
;         G_LOAD(A0, B0, 0);
;         G_STORE(0);
;         G_LOAD(A0, B0, 1);
;         __syncthreads();
;     }
;     for (int idx = idx0; idx < perX; idx += nbx) {
;         int mt, nt; tile_of(idx, mt, nt);
;         int mtn, ntn; tile_of(idx + nbx < perX ? idx + nbx : idx, mtn, ntn);
;         const bf16_t* Ag = A + (size_t)(mt * 128 + lrow) * K + lcc * 8;
;         const bf16_t* Bg = Bt + (size_t)(nt * 256 + lrowp) * K + lcc * 8;
;         const bf16_t* An = A + (size_t)(mtn * 128 + lrow) * K + lcc * 8;
;         const bf16_t* Bn = Bt + (size_t)(ntn * 256 + lrowp) * K + lcc * 8;
;         f32x4 acc[4][8];
; #pragma unroll
;         for (int i = 0; i < 4; ++i)
; #pragma unroll
;             for (int j = 0; j < 8; ++j) {
;                 if (EPI == 2)
;                     acc[i][j] = *(const f32x4*)(xin + (size_t)(mt * 128 + wr * 64 + i * 16 + fr) * Nn + nt * 256 + wc * 128 + 32 * (j >> 1) + 8 * fq + 4 * (j & 1));
;                 else acc[i][j] = (f32x4){0.f, 0.f, 0.f, 0.f};
;             }
;         for (int kt = 0; kt < nk; ++kt) {
;             const int buf = kt & 1;
;             const bf16_t* a_ = sA + buf * 128 * 40 + (wr * 64 + fr) * 40 + fq * 8;
;             const bf16_t* b_ = sB + buf * 256 * 40 + (wc * 128 + fr) * 40 + fq * 8;
;             bf16x8 af[4];
; #pragma unroll
;             for (int i = 0; i < 4; ++i) af[i] = *(const bf16x8*)(a_ + i * 16 * 40);
; #pragma unroll
;             for (int jh = 0; jh < 2; ++jh) {
;                 bf16x8 bfr[4];
; #pragma unroll
;                 for (int j = 0; j < 4; ++j) bfr[j] = *(const bf16x8*)(b_ + (jh * 4 + j) * 16 * 40);
; #pragma unroll
;                 for (int i = 0; i < 4; ++i)
; #pragma unroll
;                     for (int j = 0; j < 4; ++j) acc[i][jh * 4 + j] = mfma(bfr[j], af[i], acc[i][jh * 4 + j]);
;             }
;             G_STORE(buf ^ 1);
;             {
;                 const bool cur = kt + 2 < nk;
;                 const bf16_t* pa = cur ? Ag : An; const bf16_t* pb = cur ? Bg : Bn;
;                 const int st = cur ? kt + 2 : kt + 2 - nk;
;                 G_LOAD(pa, pb, st);
.LBB0_853:
	v_readlane_b32 s15, v253, 4
	v_readlane_b32 s16, v253, 6
	v_readlane_b32 s17, v253, 5
	s_nop 3
	s_cmp_eq_u32 s17, 0
	s_cbranch_scc1 .Lg853_entry
	v_and_b32_e32 v8, 63, v210
	v_lshrrev_b32_e32 v9, 6, v210
	s_nop 0
	v_readfirstlane_b32 s17, v9
	v_lshrrev_b32_e32 v9, 4, v8
	v_sub_u32_e32 v10, 0, v9
	v_and_b32_e32 v10, 3, v10
	v_and_b32_e32 v11, 3, v8
	v_xor_b32_e32 v11, v11, v10
	v_lshrrev_b32_e32 v12, 2, v8
	v_lshlrev_b32_e32 v0, 13, v12
	v_lshl_add_u32 v0, v11, 4, v0
	s_lshl_b32 vcc_lo, s17, 18
	v_add_u32_e32 v0, vcc_lo, v0
	v_add_u32_e32 v0, 0x1000, v0
	v_add_u32_e32 v1, 0x1fc00, v0
	v_and_b32_e32 v13, 3, v12
	v_lshl_add_u32 v13, v9, 3, v13
	v_lshlrev_b32_e32 v2, 13, v13
	v_lshl_add_u32 v2, v11, 4, v2
	s_lshl_b32 vcc_lo, s17, 19
	v_add_u32_e32 v2, vcc_lo, v2
	v_add_u32_e32 v2, 0x800, v2
	v_add_u32_e32 v3, 0x7c00, v2
	v_add_u32_e32 v4, 0x40800, v2
	v_add_u32_e32 v5, 0x48400, v2
	v_and_b32_e32 v10, 15, v8
	v_lshrrev_b32_e32 v11, 2, v10
	v_sub_u32_e32 v11, 0, v11
	v_and_b32_e32 v11, 3, v11
	v_xor_b32_e32 v11, v9, v11
	v_lshlrev_b32_e32 v6, 6, v10
	v_lshl_add_u32 v6, v11, 4, v6
	s_lshr_b32 vcc_lo, s17, 1
	s_mul_i32 vcc_lo, vcc_lo, 0x3000
	s_and_b32 vcc_hi, s17, 1
	s_mul_i32 vcc_hi, vcc_hi, 0x3000
	s_add_u32 vcc_hi, vcc_hi, 0x800
	v_add_u32_e32 v7, vcc_hi, v6
	v_add_u32_e32 v6, vcc_lo, v6
	s_mul_i32 s16, s17, 0x1800
	v_writelane_b32 v253, s16, 6
	v_writelane_b32 v253, 0, 5
	v_readlane_b32 vcc_lo, v253, 0
	v_readlane_b32 vcc_hi, v253, 1
	s_lshl_b32 s17, s6, 20
	s_nop 1
	s_add_u32 s98, vcc_lo, s17
	s_addc_u32 s99, vcc_hi, 0
	s_sub_u32 s98, s98, 0x1000
	s_subb_u32 s99, s99, 0
	v_readlane_b32 vcc_lo, v253, 2
	v_readlane_b32 vcc_hi, v253, 3
	s_lshl_b32 s17, s7, 21
	s_nop 1
	s_add_u32 s100, vcc_lo, s17
	s_addc_u32 s101, vcc_hi, 0
	s_sub_u32 s100, s100, 0x1000
	s_subb_u32 s101, s101, 0
	s_add_u32 m0, s15, s16
	s_nop 0
	global_load_lds_dwordx4 v0, s[98:99]
	global_load_lds_dwordx4 v1, s[98:99] offset:1024
	global_load_lds_dwordx4 v2, s[100:101] offset:2048
	global_load_lds_dwordx4 v3, s[100:101] offset:3072
	s_add_u32 m0, m0, 0x1000
	s_nop 0
	global_load_lds_dwordx4 v4, s[100:101]
	global_load_lds_dwordx4 v5, s[100:101] offset:1024
	s_add_u32 s98, s98, 64
	s_addc_u32 s99, s99, 0
	s_add_u32 s100, s100, 64
	s_addc_u32 s101, s101, 0
	s_add_u32 s17, s15, 0x6000
	s_cmp_eq_u32 s17, 0x12000
	s_cselect_b32 s17, 0, s17
	s_add_u32 m0, s17, s16
	s_nop 0
	global_load_lds_dwordx4 v0, s[98:99]
	global_load_lds_dwordx4 v1, s[98:99] offset:1024
	global_load_lds_dwordx4 v2, s[100:101] offset:2048
	global_load_lds_dwordx4 v3, s[100:101] offset:3072
	s_add_u32 m0, m0, 0x1000
	s_nop 0
	global_load_lds_dwordx4 v4, s[100:101]
	global_load_lds_dwordx4 v5, s[100:101] offset:1024
	s_add_u32 s98, s98, 64
	s_addc_u32 s99, s99, 0
	s_add_u32 s100, s100, 64
	s_addc_u32 s101, s101, 0
	s_add_u32 s17, s17, 0x6000
	s_cmp_eq_u32 s17, 0x12000
	s_cselect_b32 s17, 0, s17
	s_add_u32 m0, s17, s16
	s_nop 0
	global_load_lds_dwordx4 v0, s[98:99]
	global_load_lds_dwordx4 v1, s[98:99] offset:1024
	global_load_lds_dwordx4 v2, s[100:101] offset:2048
	global_load_lds_dwordx4 v3, s[100:101] offset:3072
	s_add_u32 m0, m0, 0x1000
	s_nop 0
	global_load_lds_dwordx4 v4, s[100:101]
	global_load_lds_dwordx4 v5, s[100:101] offset:1024
	s_add_u32 s98, s98, 64
	s_addc_u32 s99, s99, 0
	s_add_u32 s100, s100, 64
	s_addc_u32 s101, s101, 0
.Lg853_entry:
	s_mov_b32 s14, 0
	s_waitcnt vmcnt(0)
	s_barrier
	v_add_u32_e32 v8, s15, v6
	v_add_u32_e32 v9, s15, v7
	ds_read_b128 v[174:177], v9
	ds_read_b128 v[192:195], v9 offset:1024
	ds_read_b128 v[196:199], v9 offset:2048
	ds_read_b128 v[200:203], v9 offset:3072
	ds_read_b128 v[10:13], v8
	ds_read_b128 v[14:17], v8 offset:1024
	ds_read_b128 v[18:21], v8 offset:6144
	ds_read_b128 v[154:157], v8 offset:7168
	ds_read_b128 v[204:207], v9 offset:6144
	ds_read_b128 v[232:235], v9 offset:7168
	ds_read_b128 v[236:239], v9 offset:8192
	ds_read_b128 v[240:243], v9 offset:9216
.Lg853_top:
	s_waitcnt lgkmcnt(4)
	v_mfma_f32_16x16x32_bf16 v[148:151], v[174:177], v[10:13], v[148:151]
	v_mfma_f32_16x16x32_bf16 v[116:119], v[174:177], v[14:17], v[116:119]
	v_mfma_f32_16x16x32_bf16 v[84:87], v[174:177], v[18:21], v[84:87]
	v_mfma_f32_16x16x32_bf16 v[52:55], v[174:177], v[154:157], v[52:55]
	v_mfma_f32_16x16x32_bf16 v[144:147], v[192:195], v[10:13], v[144:147]
	v_mfma_f32_16x16x32_bf16 v[112:115], v[192:195], v[14:17], v[112:115]
	v_mfma_f32_16x16x32_bf16 v[80:83], v[192:195], v[18:21], v[80:83]
	v_mfma_f32_16x16x32_bf16 v[48:51], v[192:195], v[154:157], v[48:51]
	v_mfma_f32_16x16x32_bf16 v[140:143], v[196:199], v[10:13], v[140:143]
	v_mfma_f32_16x16x32_bf16 v[108:111], v[196:199], v[14:17], v[108:111]
	v_mfma_f32_16x16x32_bf16 v[76:79], v[196:199], v[18:21], v[76:79]
	v_mfma_f32_16x16x32_bf16 v[44:47], v[196:199], v[154:157], v[44:47]
	v_mfma_f32_16x16x32_bf16 v[136:139], v[200:203], v[10:13], v[136:139]
	v_mfma_f32_16x16x32_bf16 v[104:107], v[200:203], v[14:17], v[104:107]
	v_mfma_f32_16x16x32_bf16 v[72:75], v[200:203], v[18:21], v[72:75]
	v_mfma_f32_16x16x32_bf16 v[40:43], v[200:203], v[154:157], v[40:43]
	s_waitcnt vmcnt(6)
	s_waitcnt lgkmcnt(0)
	s_barrier
	s_add_u32 s17, s15, 0x6000
	s_cmp_eq_u32 s17, 0x12000
	s_cselect_b32 s17, 0, s17
	v_add_u32_e32 v8, s17, v6
	v_add_u32_e32 v9, s17, v7
	ds_read_b128 v[174:177], v9
	ds_read_b128 v[192:195], v9 offset:1024
	ds_read_b128 v[196:199], v9 offset:2048
	ds_read_b128 v[200:203], v9 offset:3072
	s_cmp_eq_u32 s14, 125
	s_cbranch_scc1 .Lg853_sw
; DI f32x4 mfma(bf16x8 a, bf16x8 b, f32x4 c) { return __builtin_amdgcn_mfma_f32_16x16x32_bf16(a, b, c, 0, 0, 0); }
; #define G_LOAD(PA, PB, STEP) do { _Pragma("unroll") for (int i_ = 0; i_ < 2; ++i_) ra[i_] = *(const u32x4*)((PA) + (size_t)(64 * i_) * K + (STEP) * 32); \
;         _Pragma("unroll") for (int i_ = 0; i_ < 4; ++i_) rb[i_] = *(const u32x4*)((PB) + (size_t)(64 * i_) * K + (STEP) * 32); } while (0)
; #define G_STORE(BUF) do { _Pragma("unroll") for (int i_ = 0; i_ < 2; ++i_) *(u32x4*)(sA + (BUF) * 128 * 40 + (lrow + 64 * i_) * 40 + lcc * 8) = ra[i_]; \
;         _Pragma("unroll") for (int i_ = 0; i_ < 4; ++i_) *(u32x4*)(sB + (BUF) * 256 * 40 + (lrow + 64 * i_) * 40 + lcc * 8) = rb[i_]; } while (0)
; template <int EPI> ...
;     ...
;         for (int kt = 0; kt < nk; ++kt) {
;             const int buf = kt & 1;
;             const bf16_t* a_ = sA + buf * 128 * 40 + (wr * 64 + fr) * 40 + fq * 8;
;             const bf16_t* b_ = sB + buf * 256 * 40 + (wc * 128 + fr) * 40 + fq * 8;
;             bf16x8 af[4];
; #pragma unroll
;             for (int i = 0; i < 4; ++i) af[i] = *(const bf16x8*)(a_ + i * 16 * 40);
; #pragma unroll
;             for (int jh = 0; jh < 2; ++jh) {
;                 bf16x8 bfr[4];
; #pragma unroll
;                 for (int j = 0; j < 4; ++j) bfr[j] = *(const bf16x8*)(b_ + (jh * 4 + j) * 16 * 40);
; #pragma unroll
;                 for (int i = 0; i < 4; ++i)
; #pragma unroll
;                     for (int j = 0; j < 4; ++j) acc[i][jh * 4 + j] = mfma(bfr[j], af[i], acc[i][jh * 4 + j]);
;             }
;             G_STORE(buf ^ 1);
;             {
;                 const bool cur = kt + 2 < nk;
;                 const bf16_t* pa = cur ? Ag : An; const bf16_t* pb = cur ? Bg : Bn;
;                 const int st = cur ? kt + 2 : kt + 2 - nk;
;                 G_LOAD(pa, pb, st);
;             }
;             __syncthreads();
;         }
.Lg853_swret:
	s_add_u32 m0, s15, s16
	v_mfma_f32_16x16x32_bf16 v[132:135], v[204:207], v[10:13], v[132:135]
	global_load_lds_dwordx4 v0, s[98:99]
	v_mfma_f32_16x16x32_bf16 v[128:131], v[232:235], v[10:13], v[128:131]
	v_mfma_f32_16x16x32_bf16 v[124:127], v[236:239], v[10:13], v[124:127]
	global_load_lds_dwordx4 v1, s[98:99] offset:1024
	v_mfma_f32_16x16x32_bf16 v[120:123], v[240:243], v[10:13], v[120:123]
	ds_read_b128 v[10:13], v8
	v_mfma_f32_16x16x32_bf16 v[100:103], v[204:207], v[14:17], v[100:103]
	global_load_lds_dwordx4 v2, s[100:101] offset:2048
	v_mfma_f32_16x16x32_bf16 v[96:99], v[232:235], v[14:17], v[96:99]
	v_mfma_f32_16x16x32_bf16 v[92:95], v[236:239], v[14:17], v[92:95]
	global_load_lds_dwordx4 v3, s[100:101] offset:3072
	v_mfma_f32_16x16x32_bf16 v[88:91], v[240:243], v[14:17], v[88:91]
	ds_read_b128 v[14:17], v8 offset:1024
	v_mfma_f32_16x16x32_bf16 v[68:71], v[204:207], v[18:21], v[68:71]
	s_add_u32 m0, m0, 0x1000
	v_mfma_f32_16x16x32_bf16 v[64:67], v[232:235], v[18:21], v[64:67]
	global_load_lds_dwordx4 v4, s[100:101]
	v_mfma_f32_16x16x32_bf16 v[60:63], v[236:239], v[18:21], v[60:63]
	v_mfma_f32_16x16x32_bf16 v[56:59], v[240:243], v[18:21], v[56:59]
	ds_read_b128 v[18:21], v8 offset:6144
	v_mfma_f32_16x16x32_bf16 v[36:39], v[204:207], v[154:157], v[36:39]
	global_load_lds_dwordx4 v5, s[100:101] offset:1024
	v_mfma_f32_16x16x32_bf16 v[32:35], v[232:235], v[154:157], v[32:35]
	v_mfma_f32_16x16x32_bf16 v[28:31], v[236:239], v[154:157], v[28:31]
	v_mfma_f32_16x16x32_bf16 v[24:27], v[240:243], v[154:157], v[24:27]
	ds_read_b128 v[154:157], v8 offset:7168
	ds_read_b128 v[204:207], v9 offset:6144
	ds_read_b128 v[232:235], v9 offset:7168
	ds_read_b128 v[236:239], v9 offset:8192
	ds_read_b128 v[240:243], v9 offset:9216
	s_add_u32 s98, s98, 64
	s_addc_u32 s99, s99, 0
	s_add_u32 s100, s100, 64
	s_addc_u32 s101, s101, 0
	s_add_u32 s15, s15, 0x6000
	s_cmp_eq_u32 s15, 0x12000
	s_cselect_b32 s15, 0, s15
	s_add_u32 s14, s14, 1
	s_cmp_lt_u32 s14, 127
	s_cbranch_scc1 .Lg853_top
	s_waitcnt lgkmcnt(4)
	v_mfma_f32_16x16x32_bf16 v[148:151], v[174:177], v[10:13], v[148:151]
	v_mfma_f32_16x16x32_bf16 v[116:119], v[174:177], v[14:17], v[116:119]
	v_mfma_f32_16x16x32_bf16 v[84:87], v[174:177], v[18:21], v[84:87]
	v_mfma_f32_16x16x32_bf16 v[52:55], v[174:177], v[154:157], v[52:55]
	v_mfma_f32_16x16x32_bf16 v[144:147], v[192:195], v[10:13], v[144:147]
	v_mfma_f32_16x16x32_bf16 v[112:115], v[192:195], v[14:17], v[112:115]
	v_mfma_f32_16x16x32_bf16 v[80:83], v[192:195], v[18:21], v[80:83]
	v_mfma_f32_16x16x32_bf16 v[48:51], v[192:195], v[154:157], v[48:51]
	v_mfma_f32_16x16x32_bf16 v[140:143], v[196:199], v[10:13], v[140:143]
	v_mfma_f32_16x16x32_bf16 v[108:111], v[196:199], v[14:17], v[108:111]
	v_mfma_f32_16x16x32_bf16 v[76:79], v[196:199], v[18:21], v[76:79]
	v_mfma_f32_16x16x32_bf16 v[44:47], v[196:199], v[154:157], v[44:47]
	v_mfma_f32_16x16x32_bf16 v[136:139], v[200:203], v[10:13], v[136:139]
	v_mfma_f32_16x16x32_bf16 v[104:107], v[200:203], v[14:17], v[104:107]
	v_mfma_f32_16x16x32_bf16 v[72:75], v[200:203], v[18:21], v[72:75]
	v_mfma_f32_16x16x32_bf16 v[40:43], v[200:203], v[154:157], v[40:43]
	s_waitcnt vmcnt(6)
	s_waitcnt lgkmcnt(0)
	s_barrier
	s_add_u32 m0, s15, s16
	v_mfma_f32_16x16x32_bf16 v[132:135], v[204:207], v[10:13], v[132:135]
	global_load_lds_dwordx4 v0, s[98:99]
	v_mfma_f32_16x16x32_bf16 v[128:131], v[232:235], v[10:13], v[128:131]
	v_mfma_f32_16x16x32_bf16 v[124:127], v[236:239], v[10:13], v[124:127]
	global_load_lds_dwordx4 v1, s[98:99] offset:1024
	v_mfma_f32_16x16x32_bf16 v[120:123], v[240:243], v[10:13], v[120:123]
	v_mfma_f32_16x16x32_bf16 v[100:103], v[204:207], v[14:17], v[100:103]
	global_load_lds_dwordx4 v2, s[100:101] offset:2048
	v_mfma_f32_16x16x32_bf16 v[96:99], v[232:235], v[14:17], v[96:99]
	v_mfma_f32_16x16x32_bf16 v[92:95], v[236:239], v[14:17], v[92:95]
	global_load_lds_dwordx4 v3, s[100:101] offset:3072
	v_mfma_f32_16x16x32_bf16 v[88:91], v[240:243], v[14:17], v[88:91]
	v_mfma_f32_16x16x32_bf16 v[68:71], v[204:207], v[18:21], v[68:71]
	s_add_u32 m0, m0, 0x1000
	v_mfma_f32_16x16x32_bf16 v[64:67], v[232:235], v[18:21], v[64:67]
	global_load_lds_dwordx4 v4, s[100:101]
	v_mfma_f32_16x16x32_bf16 v[60:63], v[236:239], v[18:21], v[60:63]
	v_mfma_f32_16x16x32_bf16 v[56:59], v[240:243], v[18:21], v[56:59]
	v_mfma_f32_16x16x32_bf16 v[36:39], v[204:207], v[154:157], v[36:39]
	global_load_lds_dwordx4 v5, s[100:101] offset:1024
	v_mfma_f32_16x16x32_bf16 v[32:35], v[232:235], v[154:157], v[32:35]
	v_mfma_f32_16x16x32_bf16 v[28:31], v[236:239], v[154:157], v[28:31]
	v_mfma_f32_16x16x32_bf16 v[24:27], v[240:243], v[154:157], v[24:27]
	s_add_u32 s98, s98, 64
	s_addc_u32 s99, s99, 0
	s_add_u32 s100, s100, 64
	s_addc_u32 s101, s101, 0
	s_add_u32 s15, s15, 0x6000
	s_cmp_eq_u32 s15, 0x12000
	s_cselect_b32 s15, 0, s15
	s_add_u32 s14, s14, 1
	s_branch .Lg853_end
; DI unsigned pk2(float lo, float hi) { f32x2 v = {lo, hi}; bf16x2_t r = __builtin_convertvector(v, bf16x2_t); return __builtin_bit_cast(unsigned, r); }
; template <int EPI> ...
;     ...
;         int mtn, ntn; tile_of(idx + nbx < perX ? idx + nbx : idx, mtn, ntn);
;         const bf16_t* Ag = A + (size_t)(mt * 128 + lrow) * K + lcc * 8;
;         const bf16_t* Bg = Bt + (size_t)(nt * 256 + lrowp) * K + lcc * 8;
;         const bf16_t* An = A + (size_t)(mtn * 128 + lrow) * K + lcc * 8;
;         const bf16_t* Bn = Bt + (size_t)(ntn * 256 + lrowp) * K + lcc * 8;
;     ...
;                 } else {
;                     *(f32x4*)(xout + (size_t)m * Nn + n0) = v0;
;                     *(f32x4*)(xout + (size_t)m * Nn + n0 + 4) = v1;
;                     if (hb) {
;                         const f32x4 g0 = *(const f32x4*)(gn + n0), g1 = *(const f32x4*)(gn + n0 + 4);
;                         u32x4 o4; o4[0] = pk2(v0[0] * g0[0], v0[1] * g0[1]); o4[1] = pk2(v0[2] * g0[2], v0[3] * g0[3]);
;                         o4[2] = pk2(v1[0] * g1[0], v1[1] * g1[1]); o4[3] = pk2(v1[2] * g1[2], v1[3] * g1[3]);
;                         *(u32x4*)(hb + (size_t)m * Nn + n0) = o4;
;                         sq += v0[0] * v0[0] + v0[1] * v0[1] + v0[2] * v0[2] + v0[3] * v0[3] + v1[0] * v1[0] + v1[1] * v1[1] + v1[2] * v1[2] + v1[3] * v1[3];
;                     }
.Lg853_sw:
	v_readlane_b32 vcc_lo, v253, 0
	v_readlane_b32 vcc_hi, v253, 1
	s_lshl_b32 s17, s11, 20
	s_nop 1
	s_add_u32 s98, vcc_lo, s17
	s_addc_u32 s99, vcc_hi, 0
	s_sub_u32 s98, s98, 0x1000
	s_subb_u32 s99, s99, 0
	v_readlane_b32 vcc_lo, v253, 2
	v_readlane_b32 vcc_hi, v253, 3
	s_lshl_b32 s17, s13, 21
	s_nop 1
	s_add_u32 s100, vcc_lo, s17
	s_addc_u32 s101, vcc_hi, 0
	s_sub_u32 s100, s100, 0x1000
	s_subb_u32 s101, s101, 0
	s_branch .Lg853_swret
.Lg853_end:
	v_writelane_b32 v253, s15, 4
	v_readlane_b32 s52, v251, 34
	v_readlane_b32 s53, v251, 35
	v_readlane_b32 s54, v251, 36
	v_readlane_b32 s55, v251, 37
	v_readlane_b32 s56, v251, 38
	v_readlane_b32 s57, v251, 39
	v_readlane_b32 s58, v251, 40
	v_readlane_b32 s59, v251, 41
	v_readlane_b32 s60, v251, 42
	v_readlane_b32 s61, v251, 43
	v_readlane_b32 s62, v251, 44
	v_readlane_b32 s63, v251, 45
	v_readlane_b32 s64, v251, 46
	v_readlane_b32 s65, v251, 47
	v_readlane_b32 s66, v251, 48
	v_readlane_b32 s67, v251, 49
	v_or_b32_e32 v185, s10, v184
	v_lshl_add_u64 v[164:165], s[56:57], 0, v[164:165]
	v_readlane_b32 s52, v250, 51
	v_readlane_b32 s6, v250, 42
	v_lshlrev_b64 v[174:175], 11, v[170:171]
	v_readlane_b32 s54, v250, 53
	v_readlane_b32 s55, v250, 54
	v_lshlrev_b32_e32 v188, 2, v185
	v_readlane_b32 s7, v250, 43
	v_lshl_add_u64 v[174:175], s[54:55], 0, v[174:175]
	v_lshl_add_u64 v[176:177], v[164:165], 0, v[188:189]
	s_and_b64 vcc, exec, s[6:7]
	v_lshlrev_b32_e32 v164, 1, v185
	v_readlane_b32 s53, v250, 52
	v_readlane_b32 s56, v250, 55
	v_readlane_b32 s57, v250, 56
	v_readlane_b32 s58, v250, 57
	v_readlane_b32 s59, v250, 58
	v_readlane_b32 s60, v250, 59
	v_readlane_b32 s61, v250, 60
	v_readlane_b32 s62, v250, 61
	v_readlane_b32 s63, v250, 62
	v_readlane_b32 s64, v250, 63
	v_readlane_b32 s65, v249, 0
	v_readlane_b32 s66, v249, 1
	v_readlane_b32 s67, v249, 2
	global_store_dwordx4 v[176:177], v[148:151], off
	global_store_dwordx4 v[176:177], v[144:147], off offset:16
	s_cbranch_vccz .LBB0_856
	v_readlane_b32 s6, v250, 40
	v_readlane_b32 s7, v250, 41
	s_nop 4
	global_load_dwordx4 v[192:195], v188, s[6:7] offset:16
	global_load_dwordx4 v[196:199], v188, s[6:7]
	v_mov_b32_e32 v165, v189
	s_waitcnt vmcnt(1)
	v_pk_mul_f32 v[192:193], v[144:145], v[192:193]
	s_waitcnt vmcnt(0)
	v_pk_mul_f32 v[196:197], v[148:149], v[196:197]
	v_pk_mul_f32 v[148:149], v[148:149], v[148:149]
	v_pk_mul_f32 v[186:187], v[150:151], v[198:199]
	v_pk_mul_f32 v[150:151], v[150:151], v[150:151]
	v_add_f32_e32 v148, v148, v149
	v_add_f32_e32 v148, v150, v148
	v_pk_mul_f32 v[144:145], v[144:145], v[144:145]
	v_add_f32_e32 v148, v151, v148
	v_add_f32_e32 v144, v144, v148
	v_cvt_pk_bf16_f32 v196, v196, v197
	v_cvt_pk_bf16_f32 v197, v186, v187
	v_pk_mul_f32 v[186:187], v[146:147], v[194:195]
	v_pk_mul_f32 v[146:147], v[146:147], v[146:147]
	v_add_f32_e32 v144, v145, v144
	v_add_f32_e32 v144, v146, v144
	v_cvt_pk_bf16_f32 v198, v192, v193
	v_cvt_pk_bf16_f32 v199, v186, v187
	v_lshl_add_u64 v[186:187], v[174:175], 0, v[164:165]
	v_add_f32_e32 v145, v147, v144
	global_store_dwordx4 v[186:187], v[196:199], off
	s_branch .LBB0_857
